# prologue weight conversion: the 32 strided f32 weight loads of an item issued up front under their lane masks (were 32 dependent load-wait round trips)
# speedup vs baseline: 1.0216x; 1.0216x over previous
.LBB0_27:
	s_mul_i32 s2, s17, 0x50
	s_mul_hi_u32 s3, s16, 0x50
	s_add_i32 s3, s3, s2
	s_mul_i32 s2, s16, 0x50
	s_add_u32 s36, s0, s2
	s_addc_u32 s37, s1, s3
	s_load_dword s2, s[36:37], 0x150
	s_load_dword s50, s[36:37], 0x160
	s_load_dword s4, s[36:37], 0x168
	s_load_dwordx4 s[16:19], s[36:37], 0x140
	s_load_dwordx4 s[12:15], s[36:37], 0x120
	s_load_dwordx2 s[40:41], s[36:37], 0x130
	s_waitcnt lgkmcnt(0)
	s_ashr_i32 s3, s2, 31
	s_lshr_b32 s3, s3, 27
	s_add_i32 s2, s2, s3
	s_ashr_i32 s2, s2, 5
	s_abs_i32 s3, s2
	v_cvt_f32_u32_e32 v32, s3
	s_sub_i32 s31, 0, s3
	s_sub_i32 s4, s43, s4
	s_abs_i32 s5, s4
	v_rcp_iflag_f32_e32 v32, v32
	s_xor_b32 s19, s4, s2
	s_ashr_i32 s19, s19, 31
	v_mov_b32_e32 v33, s13
	v_mul_f32_e32 v32, 0x4f7ffffe, v32
	v_cvt_u32_f32_e32 v32, v32
	s_nop 0
	v_readfirstlane_b32 s38, v32
	s_mul_i32 s31, s31, s38
	s_mul_hi_u32 s31, s38, s31
	s_add_i32 s38, s38, s31
	s_mul_hi_u32 s31, s5, s38
	s_mul_i32 s38, s31, s3
	s_sub_i32 s5, s5, s38
	s_add_i32 s39, s31, 1
	s_sub_i32 s38, s5, s3
	s_cmp_ge_u32 s5, s3
	s_cselect_b32 s31, s39, s31
	s_cselect_b32 s5, s38, s5
	s_add_i32 s38, s31, 1
	s_cmp_ge_u32 s5, s3
	s_cselect_b32 s3, s38, s31
	s_xor_b32 s3, s3, s19
	s_sub_i32 s3, s3, s19
	s_mul_i32 s2, s3, s2
	s_sub_i32 s49, s4, s2
	s_lshl_b32 s31, s49, 5
	s_lshl_b32 s38, s3, 6
	v_or_b32_e32 v34, s31, v89
	v_mov_b32_e32 v32, s12
	v_ashrrev_i32_e32 v35, 31, v34
	s_cmp_lg_u64 s[14:15], 0
	v_cmp_gt_i32_e64 s[4:5], s18, v34
	v_lshl_add_u64 v[32:33], v[34:35], 2, v[32:33]
	s_cselect_b64 s[2:3], -1, 0
	v_add_u32_e32 v34, s38, v66
	v_cmp_gt_i32_e32 vcc, s17, v34
	v_cndmask_b32_e64 v36, 0, 1, s[2:3]
	s_and_b64 s[18:19], s[4:5], vcc
	v_mov_b32_e32 v35, 0
	v_cmp_ne_u32_e64 s[2:3], 1, v36
	v_add_u32_e32 v232, 0, v34
	v_cmp_gt_i32_e32 vcc, s17, v232
	s_nop 0
	s_and_b64 s[94:95], s[4:5], vcc
	s_and_saveexec_b64 s[96:97], s[94:95]
	s_cbranch_execz .Lcvpf0_0
	v_mad_i64_i32 v[234:235], s[98:99], s16, v232, 0
	v_lshl_add_u64 v[234:235], v[234:235], 2, v[32:33]
	global_load_dword v200, v[234:235], off
.Lcvpf0_0:
	s_or_b64 exec, exec, s[96:97]
	v_add_u32_e32 v232, 2, v34
	v_cmp_gt_i32_e32 vcc, s17, v232
	s_nop 0
	s_and_b64 s[94:95], s[4:5], vcc
	s_and_saveexec_b64 s[96:97], s[94:95]
	s_cbranch_execz .Lcvpf0_1
	v_mad_i64_i32 v[234:235], s[98:99], s16, v232, 0
	v_lshl_add_u64 v[234:235], v[234:235], 2, v[32:33]
	global_load_dword v201, v[234:235], off
.Lcvpf0_1:
	s_or_b64 exec, exec, s[96:97]
	v_add_u32_e32 v232, 4, v34
	v_cmp_gt_i32_e32 vcc, s17, v232
	s_nop 0
	s_and_b64 s[94:95], s[4:5], vcc
	s_and_saveexec_b64 s[96:97], s[94:95]
	s_cbranch_execz .Lcvpf0_2
	v_mad_i64_i32 v[234:235], s[98:99], s16, v232, 0
	v_lshl_add_u64 v[234:235], v[234:235], 2, v[32:33]
	global_load_dword v202, v[234:235], off
.Lcvpf0_2:
	s_or_b64 exec, exec, s[96:97]
	v_add_u32_e32 v232, 6, v34
	v_cmp_gt_i32_e32 vcc, s17, v232
	s_nop 0
	s_and_b64 s[94:95], s[4:5], vcc
	s_and_saveexec_b64 s[96:97], s[94:95]
	s_cbranch_execz .Lcvpf0_3
	v_mad_i64_i32 v[234:235], s[98:99], s16, v232, 0
	v_lshl_add_u64 v[234:235], v[234:235], 2, v[32:33]
	global_load_dword v203, v[234:235], off
.Lcvpf0_3:
	s_or_b64 exec, exec, s[96:97]
	v_add_u32_e32 v232, 8, v34
	v_cmp_gt_i32_e32 vcc, s17, v232
	s_nop 0
	s_and_b64 s[94:95], s[4:5], vcc
	s_and_saveexec_b64 s[96:97], s[94:95]
	s_cbranch_execz .Lcvpf0_4
	v_mad_i64_i32 v[234:235], s[98:99], s16, v232, 0
	v_lshl_add_u64 v[234:235], v[234:235], 2, v[32:33]
	global_load_dword v204, v[234:235], off
.Lcvpf0_4:
	s_or_b64 exec, exec, s[96:97]
	v_add_u32_e32 v232, 10, v34
	v_cmp_gt_i32_e32 vcc, s17, v232
	s_nop 0
	s_and_b64 s[94:95], s[4:5], vcc
	s_and_saveexec_b64 s[96:97], s[94:95]
	s_cbranch_execz .Lcvpf0_5
	v_mad_i64_i32 v[234:235], s[98:99], s16, v232, 0
	v_lshl_add_u64 v[234:235], v[234:235], 2, v[32:33]
	global_load_dword v205, v[234:235], off
.Lcvpf0_5:
	s_or_b64 exec, exec, s[96:97]
	v_add_u32_e32 v232, 12, v34
	v_cmp_gt_i32_e32 vcc, s17, v232
	s_nop 0
	s_and_b64 s[94:95], s[4:5], vcc
	s_and_saveexec_b64 s[96:97], s[94:95]
	s_cbranch_execz .Lcvpf0_6
	v_mad_i64_i32 v[234:235], s[98:99], s16, v232, 0
	v_lshl_add_u64 v[234:235], v[234:235], 2, v[32:33]
	global_load_dword v206, v[234:235], off
.Lcvpf0_6:
	s_or_b64 exec, exec, s[96:97]
	v_add_u32_e32 v232, 14, v34
	v_cmp_gt_i32_e32 vcc, s17, v232
	s_nop 0
	s_and_b64 s[94:95], s[4:5], vcc
	s_and_saveexec_b64 s[96:97], s[94:95]
	s_cbranch_execz .Lcvpf0_7
	v_mad_i64_i32 v[234:235], s[98:99], s16, v232, 0
	v_lshl_add_u64 v[234:235], v[234:235], 2, v[32:33]
	global_load_dword v207, v[234:235], off
.Lcvpf0_7:
	s_or_b64 exec, exec, s[96:97]
	v_add_u32_e32 v232, 16, v34
	v_cmp_gt_i32_e32 vcc, s17, v232
	s_nop 0
	s_and_b64 s[94:95], s[4:5], vcc
	s_and_saveexec_b64 s[96:97], s[94:95]
	s_cbranch_execz .Lcvpf0_8
	v_mad_i64_i32 v[234:235], s[98:99], s16, v232, 0
	v_lshl_add_u64 v[234:235], v[234:235], 2, v[32:33]
	global_load_dword v208, v[234:235], off
.Lcvpf0_8:
	s_or_b64 exec, exec, s[96:97]
	v_add_u32_e32 v232, 18, v34
	v_cmp_gt_i32_e32 vcc, s17, v232
	s_nop 0
	s_and_b64 s[94:95], s[4:5], vcc
	s_and_saveexec_b64 s[96:97], s[94:95]
	s_cbranch_execz .Lcvpf0_9
	v_mad_i64_i32 v[234:235], s[98:99], s16, v232, 0
	v_lshl_add_u64 v[234:235], v[234:235], 2, v[32:33]
	global_load_dword v209, v[234:235], off
.Lcvpf0_9:
	s_or_b64 exec, exec, s[96:97]
	v_add_u32_e32 v232, 20, v34
	v_cmp_gt_i32_e32 vcc, s17, v232
	s_nop 0
	s_and_b64 s[94:95], s[4:5], vcc
	s_and_saveexec_b64 s[96:97], s[94:95]
	s_cbranch_execz .Lcvpf0_10
	v_mad_i64_i32 v[234:235], s[98:99], s16, v232, 0
	v_lshl_add_u64 v[234:235], v[234:235], 2, v[32:33]
	global_load_dword v210, v[234:235], off
.Lcvpf0_10:
	s_or_b64 exec, exec, s[96:97]
	v_add_u32_e32 v232, 22, v34
	v_cmp_gt_i32_e32 vcc, s17, v232
	s_nop 0
	s_and_b64 s[94:95], s[4:5], vcc
	s_and_saveexec_b64 s[96:97], s[94:95]
	s_cbranch_execz .Lcvpf0_11
	v_mad_i64_i32 v[234:235], s[98:99], s16, v232, 0
	v_lshl_add_u64 v[234:235], v[234:235], 2, v[32:33]
	global_load_dword v211, v[234:235], off
.Lcvpf0_11:
	s_or_b64 exec, exec, s[96:97]
	v_add_u32_e32 v232, 24, v34
	v_cmp_gt_i32_e32 vcc, s17, v232
	s_nop 0
	s_and_b64 s[94:95], s[4:5], vcc
	s_and_saveexec_b64 s[96:97], s[94:95]
	s_cbranch_execz .Lcvpf0_12
	v_mad_i64_i32 v[234:235], s[98:99], s16, v232, 0
	v_lshl_add_u64 v[234:235], v[234:235], 2, v[32:33]
	global_load_dword v212, v[234:235], off
.Lcvpf0_12:
	s_or_b64 exec, exec, s[96:97]
	v_add_u32_e32 v232, 26, v34
	v_cmp_gt_i32_e32 vcc, s17, v232
	s_nop 0
	s_and_b64 s[94:95], s[4:5], vcc
	s_and_saveexec_b64 s[96:97], s[94:95]
	s_cbranch_execz .Lcvpf0_13
	v_mad_i64_i32 v[234:235], s[98:99], s16, v232, 0
	v_lshl_add_u64 v[234:235], v[234:235], 2, v[32:33]
	global_load_dword v213, v[234:235], off
.Lcvpf0_13:
	s_or_b64 exec, exec, s[96:97]
	v_add_u32_e32 v232, 28, v34
	v_cmp_gt_i32_e32 vcc, s17, v232
	s_nop 0
	s_and_b64 s[94:95], s[4:5], vcc
	s_and_saveexec_b64 s[96:97], s[94:95]
	s_cbranch_execz .Lcvpf0_14
	v_mad_i64_i32 v[234:235], s[98:99], s16, v232, 0
	v_lshl_add_u64 v[234:235], v[234:235], 2, v[32:33]
	global_load_dword v214, v[234:235], off
.Lcvpf0_14:
	s_or_b64 exec, exec, s[96:97]
	v_add_u32_e32 v232, 30, v34
	v_cmp_gt_i32_e32 vcc, s17, v232
	s_nop 0
	s_and_b64 s[94:95], s[4:5], vcc
	s_and_saveexec_b64 s[96:97], s[94:95]
	s_cbranch_execz .Lcvpf0_15
	v_mad_i64_i32 v[234:235], s[98:99], s16, v232, 0
	v_lshl_add_u64 v[234:235], v[234:235], 2, v[32:33]
	global_load_dword v215, v[234:235], off
.Lcvpf0_15:
	s_or_b64 exec, exec, s[96:97]
	v_add_u32_e32 v232, 32, v34
	v_cmp_gt_i32_e32 vcc, s17, v232
	s_nop 0
	s_and_b64 s[94:95], s[4:5], vcc
	s_and_saveexec_b64 s[96:97], s[94:95]
	s_cbranch_execz .Lcvpf0_16
	v_mad_i64_i32 v[234:235], s[98:99], s16, v232, 0
	v_lshl_add_u64 v[234:235], v[234:235], 2, v[32:33]
	global_load_dword v216, v[234:235], off
.Lcvpf0_16:
	s_or_b64 exec, exec, s[96:97]
	v_add_u32_e32 v232, 34, v34
	v_cmp_gt_i32_e32 vcc, s17, v232
	s_nop 0
	s_and_b64 s[94:95], s[4:5], vcc
	s_and_saveexec_b64 s[96:97], s[94:95]
	s_cbranch_execz .Lcvpf0_17
	v_mad_i64_i32 v[234:235], s[98:99], s16, v232, 0
	v_lshl_add_u64 v[234:235], v[234:235], 2, v[32:33]
	global_load_dword v217, v[234:235], off
.Lcvpf0_17:
	s_or_b64 exec, exec, s[96:97]
	v_add_u32_e32 v232, 36, v34
	v_cmp_gt_i32_e32 vcc, s17, v232
	s_nop 0
	s_and_b64 s[94:95], s[4:5], vcc
	s_and_saveexec_b64 s[96:97], s[94:95]
	s_cbranch_execz .Lcvpf0_18
	v_mad_i64_i32 v[234:235], s[98:99], s16, v232, 0
	v_lshl_add_u64 v[234:235], v[234:235], 2, v[32:33]
	global_load_dword v218, v[234:235], off
.Lcvpf0_18:
	s_or_b64 exec, exec, s[96:97]
	v_add_u32_e32 v232, 38, v34
	v_cmp_gt_i32_e32 vcc, s17, v232
	s_nop 0
	s_and_b64 s[94:95], s[4:5], vcc
	s_and_saveexec_b64 s[96:97], s[94:95]
	s_cbranch_execz .Lcvpf0_19
	v_mad_i64_i32 v[234:235], s[98:99], s16, v232, 0
	v_lshl_add_u64 v[234:235], v[234:235], 2, v[32:33]
	global_load_dword v219, v[234:235], off
.Lcvpf0_19:
	s_or_b64 exec, exec, s[96:97]
	v_add_u32_e32 v232, 40, v34
	v_cmp_gt_i32_e32 vcc, s17, v232
	s_nop 0
	s_and_b64 s[94:95], s[4:5], vcc
	s_and_saveexec_b64 s[96:97], s[94:95]
	s_cbranch_execz .Lcvpf0_20
	v_mad_i64_i32 v[234:235], s[98:99], s16, v232, 0
	v_lshl_add_u64 v[234:235], v[234:235], 2, v[32:33]
	global_load_dword v220, v[234:235], off
.Lcvpf0_20:
	s_or_b64 exec, exec, s[96:97]
	v_add_u32_e32 v232, 42, v34
	v_cmp_gt_i32_e32 vcc, s17, v232
	s_nop 0
	s_and_b64 s[94:95], s[4:5], vcc
	s_and_saveexec_b64 s[96:97], s[94:95]
	s_cbranch_execz .Lcvpf0_21
	v_mad_i64_i32 v[234:235], s[98:99], s16, v232, 0
	v_lshl_add_u64 v[234:235], v[234:235], 2, v[32:33]
	global_load_dword v221, v[234:235], off
.Lcvpf0_21:
	s_or_b64 exec, exec, s[96:97]
	v_add_u32_e32 v232, 44, v34
	v_cmp_gt_i32_e32 vcc, s17, v232
	s_nop 0
	s_and_b64 s[94:95], s[4:5], vcc
	s_and_saveexec_b64 s[96:97], s[94:95]
	s_cbranch_execz .Lcvpf0_22
	v_mad_i64_i32 v[234:235], s[98:99], s16, v232, 0
	v_lshl_add_u64 v[234:235], v[234:235], 2, v[32:33]
	global_load_dword v222, v[234:235], off
.Lcvpf0_22:
	s_or_b64 exec, exec, s[96:97]
	v_add_u32_e32 v232, 46, v34
	v_cmp_gt_i32_e32 vcc, s17, v232
	s_nop 0
	s_and_b64 s[94:95], s[4:5], vcc
	s_and_saveexec_b64 s[96:97], s[94:95]
	s_cbranch_execz .Lcvpf0_23
	v_mad_i64_i32 v[234:235], s[98:99], s16, v232, 0
	v_lshl_add_u64 v[234:235], v[234:235], 2, v[32:33]
	global_load_dword v223, v[234:235], off
.Lcvpf0_23:
	s_or_b64 exec, exec, s[96:97]
	v_add_u32_e32 v232, 48, v34
	v_cmp_gt_i32_e32 vcc, s17, v232
	s_nop 0
	s_and_b64 s[94:95], s[4:5], vcc
	s_and_saveexec_b64 s[96:97], s[94:95]
	s_cbranch_execz .Lcvpf0_24
	v_mad_i64_i32 v[234:235], s[98:99], s16, v232, 0
	v_lshl_add_u64 v[234:235], v[234:235], 2, v[32:33]
	global_load_dword v224, v[234:235], off
.Lcvpf0_24:
	s_or_b64 exec, exec, s[96:97]
	v_add_u32_e32 v232, 50, v34
	v_cmp_gt_i32_e32 vcc, s17, v232
	s_nop 0
	s_and_b64 s[94:95], s[4:5], vcc
	s_and_saveexec_b64 s[96:97], s[94:95]
	s_cbranch_execz .Lcvpf0_25
	v_mad_i64_i32 v[234:235], s[98:99], s16, v232, 0
	v_lshl_add_u64 v[234:235], v[234:235], 2, v[32:33]
	global_load_dword v225, v[234:235], off
.Lcvpf0_25:
	s_or_b64 exec, exec, s[96:97]
	v_add_u32_e32 v232, 52, v34
	v_cmp_gt_i32_e32 vcc, s17, v232
	s_nop 0
	s_and_b64 s[94:95], s[4:5], vcc
	s_and_saveexec_b64 s[96:97], s[94:95]
	s_cbranch_execz .Lcvpf0_26
	v_mad_i64_i32 v[234:235], s[98:99], s16, v232, 0
	v_lshl_add_u64 v[234:235], v[234:235], 2, v[32:33]
	global_load_dword v226, v[234:235], off
.Lcvpf0_26:
	s_or_b64 exec, exec, s[96:97]
	v_add_u32_e32 v232, 54, v34
	v_cmp_gt_i32_e32 vcc, s17, v232
	s_nop 0
	s_and_b64 s[94:95], s[4:5], vcc
	s_and_saveexec_b64 s[96:97], s[94:95]
	s_cbranch_execz .Lcvpf0_27
	v_mad_i64_i32 v[234:235], s[98:99], s16, v232, 0
	v_lshl_add_u64 v[234:235], v[234:235], 2, v[32:33]
	global_load_dword v227, v[234:235], off
.Lcvpf0_27:
	s_or_b64 exec, exec, s[96:97]
	v_add_u32_e32 v232, 56, v34
	v_cmp_gt_i32_e32 vcc, s17, v232
	s_nop 0
	s_and_b64 s[94:95], s[4:5], vcc
	s_and_saveexec_b64 s[96:97], s[94:95]
	s_cbranch_execz .Lcvpf0_28
	v_mad_i64_i32 v[234:235], s[98:99], s16, v232, 0
	v_lshl_add_u64 v[234:235], v[234:235], 2, v[32:33]
	global_load_dword v228, v[234:235], off
.Lcvpf0_28:
	s_or_b64 exec, exec, s[96:97]
	v_add_u32_e32 v232, 58, v34
	v_cmp_gt_i32_e32 vcc, s17, v232
	s_nop 0
	s_and_b64 s[94:95], s[4:5], vcc
	s_and_saveexec_b64 s[96:97], s[94:95]
	s_cbranch_execz .Lcvpf0_29
	v_mad_i64_i32 v[234:235], s[98:99], s16, v232, 0
	v_lshl_add_u64 v[234:235], v[234:235], 2, v[32:33]
	global_load_dword v229, v[234:235], off
.Lcvpf0_29:
	s_or_b64 exec, exec, s[96:97]
	v_add_u32_e32 v232, 60, v34
	v_cmp_gt_i32_e32 vcc, s17, v232
	s_nop 0
	s_and_b64 s[94:95], s[4:5], vcc
	s_and_saveexec_b64 s[96:97], s[94:95]
	s_cbranch_execz .Lcvpf0_30
	v_mad_i64_i32 v[234:235], s[98:99], s16, v232, 0
	v_lshl_add_u64 v[234:235], v[234:235], 2, v[32:33]
	global_load_dword v230, v[234:235], off
.Lcvpf0_30:
	s_or_b64 exec, exec, s[96:97]
	v_add_u32_e32 v232, 62, v34
	v_cmp_gt_i32_e32 vcc, s17, v232
	s_nop 0
	s_and_b64 s[94:95], s[4:5], vcc
	s_and_saveexec_b64 s[96:97], s[94:95]
	s_cbranch_execz .Lcvpf0_31
	v_mad_i64_i32 v[234:235], s[98:99], s16, v232, 0
	v_lshl_add_u64 v[234:235], v[234:235], 2, v[32:33]
	global_load_dword v231, v[234:235], off
.Lcvpf0_31:
	s_or_b64 exec, exec, s[96:97]
	s_and_saveexec_b64 s[12:13], s[18:19]
	s_cbranch_execz .LBB0_39
	s_waitcnt vmcnt(0)
	v_mov_b32_e32 v36, v200
	s_and_b64 vcc, exec, s[2:3]
	v_ashrrev_i32_e32 v35, 31, v34
	s_cbranch_vccnz .LBB0_31
	v_lshl_add_u64 v[38:39], v[34:35], 2, s[14:15]
	global_load_dword v37, v[38:39], off
	s_cmp_lt_i32 s50, 3
	s_mov_b64 s[18:19], -1
	s_cbranch_scc0 .LBB0_32

.LBB0_39:
	s_or_b64 exec, exec, s[12:13]
	v_add_u32_e32 v36, 2, v34
	v_cmp_gt_i32_e32 vcc, s17, v36
	ds_write_b32 v99, v35
	s_and_b64 s[18:19], s[4:5], vcc
	v_mov_b32_e32 v35, 0
	s_and_saveexec_b64 s[12:13], s[18:19]
	s_cbranch_execz .LBB0_51
	s_waitcnt vmcnt(0)
	v_mov_b32_e32 v35, v201
	s_and_b64 vcc, exec, s[2:3]
	s_cbranch_vccnz .LBB0_43
	s_ashr_i32 s39, s38, 31
	v_lshl_add_u64 v[36:37], s[38:39], 0, v[66:67]
	v_lshl_add_u64 v[36:37], v[36:37], 2, s[14:15]
	global_load_dword v36, v[36:37], off offset:8
	s_cmp_lt_i32 s50, 3
	s_mov_b64 s[18:19], -1
	s_cbranch_scc0 .LBB0_44

.LBB0_51:
	s_or_b64 exec, exec, s[12:13]
	v_add_u32_e32 v36, 4, v34
	v_cmp_gt_i32_e32 vcc, s17, v36
	ds_write_b32 v99, v35 offset:264
	s_and_b64 s[18:19], s[4:5], vcc
	v_mov_b32_e32 v35, 0
	s_and_saveexec_b64 s[12:13], s[18:19]
	s_cbranch_execz .LBB0_63
	s_waitcnt vmcnt(0)
	v_mov_b32_e32 v35, v202
	s_and_b64 vcc, exec, s[2:3]
	s_cbranch_vccnz .LBB0_55
	s_ashr_i32 s39, s38, 31
	v_lshl_add_u64 v[36:37], s[38:39], 0, v[66:67]
	v_lshl_add_u64 v[36:37], v[36:37], 2, s[14:15]
	global_load_dword v36, v[36:37], off offset:16
	s_cmp_lt_i32 s50, 3
	s_mov_b64 s[18:19], -1
	s_cbranch_scc0 .LBB0_56

.LBB0_63:
	s_or_b64 exec, exec, s[12:13]
	v_add_u32_e32 v36, 6, v34
	v_cmp_gt_i32_e32 vcc, s17, v36
	ds_write_b32 v99, v35 offset:528
	s_and_b64 s[18:19], s[4:5], vcc
	v_mov_b32_e32 v35, 0
	s_and_saveexec_b64 s[12:13], s[18:19]
	s_cbranch_execz .LBB0_75
	s_waitcnt vmcnt(0)
	v_mov_b32_e32 v35, v203
	s_and_b64 vcc, exec, s[2:3]
	s_cbranch_vccnz .LBB0_67
	s_ashr_i32 s39, s38, 31
	v_lshl_add_u64 v[36:37], s[38:39], 0, v[66:67]
	v_lshl_add_u64 v[36:37], v[36:37], 2, s[14:15]
	global_load_dword v36, v[36:37], off offset:24
	s_cmp_lt_i32 s50, 3
	s_mov_b64 s[18:19], -1
	s_cbranch_scc0 .LBB0_68

.LBB0_75:
	s_or_b64 exec, exec, s[12:13]
	v_add_u32_e32 v36, 8, v34
	v_cmp_gt_i32_e32 vcc, s17, v36
	ds_write_b32 v99, v35 offset:792
	s_and_b64 s[18:19], s[4:5], vcc
	v_mov_b32_e32 v35, 0
	s_and_saveexec_b64 s[12:13], s[18:19]
	s_cbranch_execz .LBB0_87
	s_waitcnt vmcnt(0)
	v_mov_b32_e32 v35, v204
	s_and_b64 vcc, exec, s[2:3]
	s_cbranch_vccnz .LBB0_79
	s_ashr_i32 s39, s38, 31
	v_lshl_add_u64 v[36:37], s[38:39], 0, v[66:67]
	v_lshl_add_u64 v[36:37], v[36:37], 2, s[14:15]
	global_load_dword v36, v[36:37], off offset:32
	s_cmp_lt_i32 s50, 3
	s_mov_b64 s[18:19], -1
	s_cbranch_scc0 .LBB0_80

.LBB0_87:
	s_or_b64 exec, exec, s[12:13]
	v_add_u32_e32 v36, 10, v34
	v_cmp_gt_i32_e32 vcc, s17, v36
	ds_write_b32 v99, v35 offset:1056
	s_and_b64 s[18:19], s[4:5], vcc
	v_mov_b32_e32 v35, 0
	s_and_saveexec_b64 s[12:13], s[18:19]
	s_cbranch_execz .LBB0_99
	s_waitcnt vmcnt(0)
	v_mov_b32_e32 v35, v205
	s_and_b64 vcc, exec, s[2:3]
	s_cbranch_vccnz .LBB0_91
	s_ashr_i32 s39, s38, 31
	v_lshl_add_u64 v[36:37], s[38:39], 0, v[66:67]
	v_lshl_add_u64 v[36:37], v[36:37], 2, s[14:15]
	global_load_dword v36, v[36:37], off offset:40
	s_cmp_lt_i32 s50, 3
	s_mov_b64 s[18:19], -1
	s_cbranch_scc0 .LBB0_92

.LBB0_99:
	s_or_b64 exec, exec, s[12:13]
	v_add_u32_e32 v36, 12, v34
	v_cmp_gt_i32_e32 vcc, s17, v36
	ds_write_b32 v99, v35 offset:1320
	s_and_b64 s[18:19], s[4:5], vcc
	v_mov_b32_e32 v35, 0
	s_and_saveexec_b64 s[12:13], s[18:19]
	s_cbranch_execz .LBB0_111
	s_waitcnt vmcnt(0)
	v_mov_b32_e32 v35, v206
	s_and_b64 vcc, exec, s[2:3]
	s_cbranch_vccnz .LBB0_103
	s_ashr_i32 s39, s38, 31
	v_lshl_add_u64 v[36:37], s[38:39], 0, v[66:67]
	v_lshl_add_u64 v[36:37], v[36:37], 2, s[14:15]
	global_load_dword v36, v[36:37], off offset:48
	s_cmp_lt_i32 s50, 3
	s_mov_b64 s[18:19], -1
	s_cbranch_scc0 .LBB0_104

.LBB0_111:
	s_or_b64 exec, exec, s[12:13]
	v_add_u32_e32 v36, 14, v34
	v_cmp_gt_i32_e32 vcc, s17, v36
	ds_write_b32 v99, v35 offset:1584
	s_and_b64 s[18:19], s[4:5], vcc
	v_mov_b32_e32 v35, 0
	s_and_saveexec_b64 s[12:13], s[18:19]
	s_cbranch_execz .LBB0_123
	s_waitcnt vmcnt(0)
	v_mov_b32_e32 v35, v207
	s_and_b64 vcc, exec, s[2:3]
	s_cbranch_vccnz .LBB0_115
	s_ashr_i32 s39, s38, 31
	v_lshl_add_u64 v[36:37], s[38:39], 0, v[66:67]
	v_lshl_add_u64 v[36:37], v[36:37], 2, s[14:15]
	global_load_dword v36, v[36:37], off offset:56
	s_cmp_lt_i32 s50, 3
	s_mov_b64 s[18:19], -1
	s_cbranch_scc0 .LBB0_116

.LBB0_123:
	s_or_b64 exec, exec, s[12:13]
	v_add_u32_e32 v36, 16, v34
	v_cmp_gt_i32_e32 vcc, s17, v36
	ds_write_b32 v99, v35 offset:1848
	s_and_b64 s[18:19], s[4:5], vcc
	v_mov_b32_e32 v35, 0
	s_and_saveexec_b64 s[12:13], s[18:19]
	s_cbranch_execz .LBB0_135
	s_waitcnt vmcnt(0)
	v_mov_b32_e32 v35, v208
	s_and_b64 vcc, exec, s[2:3]
	s_cbranch_vccnz .LBB0_127
	s_ashr_i32 s39, s38, 31
	v_lshl_add_u64 v[36:37], s[38:39], 0, v[66:67]
	v_lshl_add_u64 v[36:37], v[36:37], 2, s[14:15]
	global_load_dword v36, v[36:37], off offset:64
	s_cmp_lt_i32 s50, 3
	s_mov_b64 s[18:19], -1
	s_cbranch_scc0 .LBB0_128

.LBB0_135:
	s_or_b64 exec, exec, s[12:13]
	v_add_u32_e32 v36, 18, v34
	v_cmp_gt_i32_e32 vcc, s17, v36
	ds_write_b32 v99, v35 offset:2112
	s_and_b64 s[18:19], s[4:5], vcc
	v_mov_b32_e32 v35, 0
	s_and_saveexec_b64 s[12:13], s[18:19]
	s_cbranch_execz .LBB0_147
	s_waitcnt vmcnt(0)
	v_mov_b32_e32 v35, v209
	s_and_b64 vcc, exec, s[2:3]
	s_cbranch_vccnz .LBB0_139
	s_ashr_i32 s39, s38, 31
	v_lshl_add_u64 v[36:37], s[38:39], 0, v[66:67]
	v_lshl_add_u64 v[36:37], v[36:37], 2, s[14:15]
	global_load_dword v36, v[36:37], off offset:72
	s_cmp_lt_i32 s50, 3
	s_mov_b64 s[18:19], -1
	s_cbranch_scc0 .LBB0_140

.LBB0_147:
	s_or_b64 exec, exec, s[12:13]
	v_add_u32_e32 v36, 20, v34
	v_cmp_gt_i32_e32 vcc, s17, v36
	ds_write_b32 v99, v35 offset:2376
	s_and_b64 s[18:19], s[4:5], vcc
	v_mov_b32_e32 v35, 0
	s_and_saveexec_b64 s[12:13], s[18:19]
	s_cbranch_execz .LBB0_159
	s_waitcnt vmcnt(0)
	v_mov_b32_e32 v35, v210
	s_and_b64 vcc, exec, s[2:3]
	s_cbranch_vccnz .LBB0_151
	s_ashr_i32 s39, s38, 31
	v_lshl_add_u64 v[36:37], s[38:39], 0, v[66:67]
	v_lshl_add_u64 v[36:37], v[36:37], 2, s[14:15]
	global_load_dword v36, v[36:37], off offset:80
	s_cmp_lt_i32 s50, 3
	s_mov_b64 s[18:19], -1
	s_cbranch_scc0 .LBB0_152

.LBB0_159:
	s_or_b64 exec, exec, s[12:13]
	v_add_u32_e32 v36, 22, v34
	v_cmp_gt_i32_e32 vcc, s17, v36
	ds_write_b32 v99, v35 offset:2640
	s_and_b64 s[18:19], s[4:5], vcc
	v_mov_b32_e32 v35, 0
	s_and_saveexec_b64 s[12:13], s[18:19]
	s_cbranch_execz .LBB0_171
	s_waitcnt vmcnt(0)
	v_mov_b32_e32 v35, v211
	s_and_b64 vcc, exec, s[2:3]
	s_cbranch_vccnz .LBB0_163
	s_ashr_i32 s39, s38, 31
	v_lshl_add_u64 v[36:37], s[38:39], 0, v[66:67]
	v_lshl_add_u64 v[36:37], v[36:37], 2, s[14:15]
	global_load_dword v36, v[36:37], off offset:88
	s_cmp_lt_i32 s50, 3
	s_mov_b64 s[18:19], -1
	s_cbranch_scc0 .LBB0_164

.LBB0_171:
	s_or_b64 exec, exec, s[12:13]
	v_add_u32_e32 v36, 24, v34
	v_cmp_gt_i32_e32 vcc, s17, v36
	ds_write_b32 v99, v35 offset:2904
	s_and_b64 s[18:19], s[4:5], vcc
	v_mov_b32_e32 v35, 0
	s_and_saveexec_b64 s[12:13], s[18:19]
	s_cbranch_execz .LBB0_183
	s_waitcnt vmcnt(0)
	v_mov_b32_e32 v35, v212
	s_and_b64 vcc, exec, s[2:3]
	s_cbranch_vccnz .LBB0_175
	s_ashr_i32 s39, s38, 31
	v_lshl_add_u64 v[36:37], s[38:39], 0, v[66:67]
	v_lshl_add_u64 v[36:37], v[36:37], 2, s[14:15]
	global_load_dword v36, v[36:37], off offset:96
	s_cmp_lt_i32 s50, 3
	s_mov_b64 s[18:19], -1
	s_cbranch_scc0 .LBB0_176

.LBB0_183:
	s_or_b64 exec, exec, s[12:13]
	v_add_u32_e32 v36, 26, v34
	v_cmp_gt_i32_e32 vcc, s17, v36
	ds_write_b32 v99, v35 offset:3168
	s_and_b64 s[18:19], s[4:5], vcc
	v_mov_b32_e32 v35, 0
	s_and_saveexec_b64 s[12:13], s[18:19]
	s_cbranch_execz .LBB0_195
	s_waitcnt vmcnt(0)
	v_mov_b32_e32 v35, v213
	s_and_b64 vcc, exec, s[2:3]
	s_cbranch_vccnz .LBB0_187
	s_ashr_i32 s39, s38, 31
	v_lshl_add_u64 v[36:37], s[38:39], 0, v[66:67]
	v_lshl_add_u64 v[36:37], v[36:37], 2, s[14:15]
	global_load_dword v36, v[36:37], off offset:104
	s_cmp_lt_i32 s50, 3
	s_mov_b64 s[18:19], -1
	s_cbranch_scc0 .LBB0_188

.LBB0_195:
	s_or_b64 exec, exec, s[12:13]
	v_add_u32_e32 v36, 28, v34
	v_cmp_gt_i32_e32 vcc, s17, v36
	ds_write_b32 v99, v35 offset:3432
	s_and_b64 s[18:19], s[4:5], vcc
	v_mov_b32_e32 v35, 0
	s_and_saveexec_b64 s[12:13], s[18:19]
	s_cbranch_execz .LBB0_207
	s_waitcnt vmcnt(0)
	v_mov_b32_e32 v35, v214
	s_and_b64 vcc, exec, s[2:3]
	s_cbranch_vccnz .LBB0_199
	s_ashr_i32 s39, s38, 31
	v_lshl_add_u64 v[36:37], s[38:39], 0, v[66:67]
	v_lshl_add_u64 v[36:37], v[36:37], 2, s[14:15]
	global_load_dword v36, v[36:37], off offset:112
	s_cmp_lt_i32 s50, 3
	s_mov_b64 s[18:19], -1
	s_cbranch_scc0 .LBB0_200

.LBB0_207:
	s_or_b64 exec, exec, s[12:13]
	v_add_u32_e32 v36, 30, v34
	v_cmp_gt_i32_e32 vcc, s17, v36
	ds_write_b32 v99, v35 offset:3696
	s_and_b64 s[18:19], s[4:5], vcc
	v_mov_b32_e32 v35, 0
	s_and_saveexec_b64 s[12:13], s[18:19]
	s_cbranch_execz .LBB0_219
	s_waitcnt vmcnt(0)
	v_mov_b32_e32 v35, v215
	s_and_b64 vcc, exec, s[2:3]
	s_cbranch_vccnz .LBB0_211
	s_ashr_i32 s39, s38, 31
	v_lshl_add_u64 v[36:37], s[38:39], 0, v[66:67]
	v_lshl_add_u64 v[36:37], v[36:37], 2, s[14:15]
	global_load_dword v36, v[36:37], off offset:120
	s_cmp_lt_i32 s50, 3
	s_mov_b64 s[18:19], -1
	s_cbranch_scc0 .LBB0_212

.LBB0_219:
	s_or_b64 exec, exec, s[12:13]
	v_add_u32_e32 v36, 32, v34
	v_cmp_gt_i32_e32 vcc, s17, v36
	ds_write_b32 v99, v35 offset:3960
	s_and_b64 s[18:19], s[4:5], vcc
	v_mov_b32_e32 v35, 0
	s_and_saveexec_b64 s[12:13], s[18:19]
	s_cbranch_execz .LBB0_231
	s_waitcnt vmcnt(0)
	v_mov_b32_e32 v35, v216
	s_and_b64 vcc, exec, s[2:3]
	s_cbranch_vccnz .LBB0_223
	s_ashr_i32 s39, s38, 31
	v_lshl_add_u64 v[36:37], s[38:39], 0, v[66:67]
	v_lshl_add_u64 v[36:37], v[36:37], 2, s[14:15]
	global_load_dword v36, v[36:37], off offset:128
	s_cmp_lt_i32 s50, 3
	s_mov_b64 s[18:19], -1
	s_cbranch_scc0 .LBB0_224

.LBB0_231:
	s_or_b64 exec, exec, s[12:13]
	v_add_u32_e32 v36, 34, v34
	v_cmp_gt_i32_e32 vcc, s17, v36
	ds_write_b32 v99, v35 offset:4224
	s_and_b64 s[18:19], s[4:5], vcc
	v_mov_b32_e32 v35, 0
	s_and_saveexec_b64 s[12:13], s[18:19]
	s_cbranch_execz .LBB0_243
	s_waitcnt vmcnt(0)
	v_mov_b32_e32 v35, v217
	s_and_b64 vcc, exec, s[2:3]
	s_cbranch_vccnz .LBB0_235
	s_ashr_i32 s39, s38, 31
	v_lshl_add_u64 v[36:37], s[38:39], 0, v[66:67]
	v_lshl_add_u64 v[36:37], v[36:37], 2, s[14:15]
	global_load_dword v36, v[36:37], off offset:136
	s_cmp_lt_i32 s50, 3
	s_mov_b64 s[18:19], -1
	s_cbranch_scc0 .LBB0_236

.LBB0_243:
	s_or_b64 exec, exec, s[12:13]
	v_add_u32_e32 v36, 36, v34
	v_cmp_gt_i32_e32 vcc, s17, v36
	ds_write_b32 v99, v35 offset:4488
	s_and_b64 s[18:19], s[4:5], vcc
	v_mov_b32_e32 v35, 0
	s_and_saveexec_b64 s[12:13], s[18:19]
	s_cbranch_execz .LBB0_255
	s_waitcnt vmcnt(0)
	v_mov_b32_e32 v35, v218
	s_and_b64 vcc, exec, s[2:3]
	s_cbranch_vccnz .LBB0_247
	s_ashr_i32 s39, s38, 31
	v_lshl_add_u64 v[36:37], s[38:39], 0, v[66:67]
	v_lshl_add_u64 v[36:37], v[36:37], 2, s[14:15]
	global_load_dword v36, v[36:37], off offset:144
	s_cmp_lt_i32 s50, 3
	s_mov_b64 s[18:19], -1
	s_cbranch_scc0 .LBB0_248

.LBB0_255:
	s_or_b64 exec, exec, s[12:13]
	v_add_u32_e32 v36, 38, v34
	v_cmp_gt_i32_e32 vcc, s17, v36
	ds_write_b32 v99, v35 offset:4752
	s_and_b64 s[18:19], s[4:5], vcc
	v_mov_b32_e32 v35, 0
	s_and_saveexec_b64 s[12:13], s[18:19]
	s_cbranch_execz .LBB0_267
	s_waitcnt vmcnt(0)
	v_mov_b32_e32 v35, v219
	s_and_b64 vcc, exec, s[2:3]
	s_cbranch_vccnz .LBB0_259
	s_ashr_i32 s39, s38, 31
	v_lshl_add_u64 v[36:37], s[38:39], 0, v[66:67]
	v_lshl_add_u64 v[36:37], v[36:37], 2, s[14:15]
	global_load_dword v36, v[36:37], off offset:152
	s_cmp_lt_i32 s50, 3
	s_mov_b64 s[18:19], -1
	s_cbranch_scc0 .LBB0_260

.LBB0_267:
	s_or_b64 exec, exec, s[12:13]
	v_add_u32_e32 v36, 40, v34
	v_cmp_gt_i32_e32 vcc, s17, v36
	ds_write_b32 v99, v35 offset:5016
	s_and_b64 s[18:19], s[4:5], vcc
	v_mov_b32_e32 v35, 0
	s_and_saveexec_b64 s[12:13], s[18:19]
	s_cbranch_execz .LBB0_279
	s_waitcnt vmcnt(0)
	v_mov_b32_e32 v35, v220
	s_and_b64 vcc, exec, s[2:3]
	s_cbranch_vccnz .LBB0_271
	s_ashr_i32 s39, s38, 31
	v_lshl_add_u64 v[36:37], s[38:39], 0, v[66:67]
	v_lshl_add_u64 v[36:37], v[36:37], 2, s[14:15]
	global_load_dword v36, v[36:37], off offset:160
	s_cmp_lt_i32 s50, 3
	s_mov_b64 s[18:19], -1
	s_cbranch_scc0 .LBB0_272

.LBB0_279:
	s_or_b64 exec, exec, s[12:13]
	v_add_u32_e32 v36, 42, v34
	v_cmp_gt_i32_e32 vcc, s17, v36
	ds_write_b32 v99, v35 offset:5280
	s_and_b64 s[18:19], s[4:5], vcc
	v_mov_b32_e32 v35, 0
	s_and_saveexec_b64 s[12:13], s[18:19]
	s_cbranch_execz .LBB0_291
	s_waitcnt vmcnt(0)
	v_mov_b32_e32 v35, v221
	s_and_b64 vcc, exec, s[2:3]
	s_cbranch_vccnz .LBB0_283
	s_ashr_i32 s39, s38, 31
	v_lshl_add_u64 v[36:37], s[38:39], 0, v[66:67]
	v_lshl_add_u64 v[36:37], v[36:37], 2, s[14:15]
	global_load_dword v36, v[36:37], off offset:168
	s_cmp_lt_i32 s50, 3
	s_mov_b64 s[18:19], -1
	s_cbranch_scc0 .LBB0_284

.LBB0_291:
	s_or_b64 exec, exec, s[12:13]
	v_add_u32_e32 v36, 44, v34
	v_cmp_gt_i32_e32 vcc, s17, v36
	ds_write_b32 v99, v35 offset:5544
	s_and_b64 s[18:19], s[4:5], vcc
	v_mov_b32_e32 v35, 0
	s_and_saveexec_b64 s[12:13], s[18:19]
	s_cbranch_execz .LBB0_303
	s_waitcnt vmcnt(0)
	v_mov_b32_e32 v35, v222
	s_and_b64 vcc, exec, s[2:3]
	s_cbranch_vccnz .LBB0_295
	s_ashr_i32 s39, s38, 31
	v_lshl_add_u64 v[36:37], s[38:39], 0, v[66:67]
	v_lshl_add_u64 v[36:37], v[36:37], 2, s[14:15]
	global_load_dword v36, v[36:37], off offset:176
	s_cmp_lt_i32 s50, 3
	s_mov_b64 s[18:19], -1
	s_cbranch_scc0 .LBB0_296

.LBB0_303:
	s_or_b64 exec, exec, s[12:13]
	v_add_u32_e32 v36, 46, v34
	v_cmp_gt_i32_e32 vcc, s17, v36
	ds_write_b32 v99, v35 offset:5808
	s_and_b64 s[18:19], s[4:5], vcc
	v_mov_b32_e32 v35, 0
	s_and_saveexec_b64 s[12:13], s[18:19]
	s_cbranch_execz .LBB0_315
	s_waitcnt vmcnt(0)
	v_mov_b32_e32 v35, v223
	s_and_b64 vcc, exec, s[2:3]
	s_cbranch_vccnz .LBB0_307
	s_ashr_i32 s39, s38, 31
	v_lshl_add_u64 v[36:37], s[38:39], 0, v[66:67]
	v_lshl_add_u64 v[36:37], v[36:37], 2, s[14:15]
	global_load_dword v36, v[36:37], off offset:184
	s_cmp_lt_i32 s50, 3
	s_mov_b64 s[18:19], -1
	s_cbranch_scc0 .LBB0_308

.LBB0_315:
	s_or_b64 exec, exec, s[12:13]
	v_add_u32_e32 v36, 48, v34
	v_cmp_gt_i32_e32 vcc, s17, v36
	ds_write_b32 v99, v35 offset:6072
	s_and_b64 s[18:19], s[4:5], vcc
	v_mov_b32_e32 v35, 0
	s_and_saveexec_b64 s[12:13], s[18:19]
	s_cbranch_execz .LBB0_327
	s_waitcnt vmcnt(0)
	v_mov_b32_e32 v35, v224
	s_and_b64 vcc, exec, s[2:3]
	s_cbranch_vccnz .LBB0_319
	s_ashr_i32 s39, s38, 31
	v_lshl_add_u64 v[36:37], s[38:39], 0, v[66:67]
	v_lshl_add_u64 v[36:37], v[36:37], 2, s[14:15]
	global_load_dword v36, v[36:37], off offset:192
	s_cmp_lt_i32 s50, 3
	s_mov_b64 s[18:19], -1
	s_cbranch_scc0 .LBB0_320

.LBB0_327:
	s_or_b64 exec, exec, s[12:13]
	v_add_u32_e32 v36, 50, v34
	v_cmp_gt_i32_e32 vcc, s17, v36
	ds_write_b32 v99, v35 offset:6336
	s_and_b64 s[18:19], s[4:5], vcc
	v_mov_b32_e32 v35, 0
	s_and_saveexec_b64 s[12:13], s[18:19]
	s_cbranch_execz .LBB0_339
	s_waitcnt vmcnt(0)
	v_mov_b32_e32 v35, v225
	s_and_b64 vcc, exec, s[2:3]
	s_cbranch_vccnz .LBB0_331
	s_ashr_i32 s39, s38, 31
	v_lshl_add_u64 v[36:37], s[38:39], 0, v[66:67]
	v_lshl_add_u64 v[36:37], v[36:37], 2, s[14:15]
	global_load_dword v36, v[36:37], off offset:200
	s_cmp_lt_i32 s50, 3
	s_mov_b64 s[18:19], -1
	s_cbranch_scc0 .LBB0_332

.LBB0_339:
	s_or_b64 exec, exec, s[12:13]
	v_add_u32_e32 v36, 52, v34
	v_cmp_gt_i32_e32 vcc, s17, v36
	ds_write_b32 v99, v35 offset:6600
	s_and_b64 s[18:19], s[4:5], vcc
	v_mov_b32_e32 v35, 0
	s_and_saveexec_b64 s[12:13], s[18:19]
	s_cbranch_execz .LBB0_351
	s_waitcnt vmcnt(0)
	v_mov_b32_e32 v35, v226
	s_and_b64 vcc, exec, s[2:3]
	s_cbranch_vccnz .LBB0_343
	s_ashr_i32 s39, s38, 31
	v_lshl_add_u64 v[36:37], s[38:39], 0, v[66:67]
	v_lshl_add_u64 v[36:37], v[36:37], 2, s[14:15]
	global_load_dword v36, v[36:37], off offset:208
	s_cmp_lt_i32 s50, 3
	s_mov_b64 s[18:19], -1
	s_cbranch_scc0 .LBB0_344

.LBB0_351:
	s_or_b64 exec, exec, s[12:13]
	v_add_u32_e32 v36, 54, v34
	v_cmp_gt_i32_e32 vcc, s17, v36
	ds_write_b32 v99, v35 offset:6864
	s_and_b64 s[18:19], s[4:5], vcc
	v_mov_b32_e32 v35, 0
	s_and_saveexec_b64 s[12:13], s[18:19]
	s_cbranch_execz .LBB0_363
	s_waitcnt vmcnt(0)
	v_mov_b32_e32 v35, v227
	s_and_b64 vcc, exec, s[2:3]
	s_cbranch_vccnz .LBB0_355
	s_ashr_i32 s39, s38, 31
	v_lshl_add_u64 v[36:37], s[38:39], 0, v[66:67]
	v_lshl_add_u64 v[36:37], v[36:37], 2, s[14:15]
	global_load_dword v36, v[36:37], off offset:216
	s_cmp_lt_i32 s50, 3
	s_mov_b64 s[18:19], -1
	s_cbranch_scc0 .LBB0_356

.LBB0_363:
	s_or_b64 exec, exec, s[12:13]
	v_add_u32_e32 v36, 56, v34
	v_cmp_gt_i32_e32 vcc, s17, v36
	ds_write_b32 v99, v35 offset:7128
	s_and_b64 s[18:19], s[4:5], vcc
	v_mov_b32_e32 v35, 0
	s_and_saveexec_b64 s[12:13], s[18:19]
	s_cbranch_execz .LBB0_375
	s_waitcnt vmcnt(0)
	v_mov_b32_e32 v35, v228
	s_and_b64 vcc, exec, s[2:3]
	s_cbranch_vccnz .LBB0_367
	s_ashr_i32 s39, s38, 31
	v_lshl_add_u64 v[36:37], s[38:39], 0, v[66:67]
	v_lshl_add_u64 v[36:37], v[36:37], 2, s[14:15]
	global_load_dword v36, v[36:37], off offset:224
	s_cmp_lt_i32 s50, 3
	s_mov_b64 s[18:19], -1
	s_cbranch_scc0 .LBB0_368

.LBB0_375:
	s_or_b64 exec, exec, s[12:13]
	v_add_u32_e32 v36, 58, v34
	v_cmp_gt_i32_e32 vcc, s17, v36
	ds_write_b32 v99, v35 offset:7392
	s_and_b64 s[18:19], s[4:5], vcc
	v_mov_b32_e32 v35, 0
	s_and_saveexec_b64 s[12:13], s[18:19]
	s_cbranch_execz .LBB0_387
	s_waitcnt vmcnt(0)
	v_mov_b32_e32 v35, v229
	s_and_b64 vcc, exec, s[2:3]
	s_cbranch_vccnz .LBB0_379
	s_ashr_i32 s39, s38, 31
	v_lshl_add_u64 v[36:37], s[38:39], 0, v[66:67]
	v_lshl_add_u64 v[36:37], v[36:37], 2, s[14:15]
	global_load_dword v36, v[36:37], off offset:232
	s_cmp_lt_i32 s50, 3
	s_mov_b64 s[18:19], -1
	s_cbranch_scc0 .LBB0_380

.LBB0_387:
	s_or_b64 exec, exec, s[12:13]
	v_add_u32_e32 v36, 60, v34
	v_cmp_gt_i32_e32 vcc, s17, v36
	ds_write_b32 v99, v35 offset:7656
	s_and_b64 s[18:19], s[4:5], vcc
	v_mov_b32_e32 v35, 0
	s_and_saveexec_b64 s[12:13], s[18:19]
	s_cbranch_execz .LBB0_399
	s_waitcnt vmcnt(0)
	v_mov_b32_e32 v35, v230
	s_and_b64 vcc, exec, s[2:3]
	s_cbranch_vccnz .LBB0_391
	s_ashr_i32 s39, s38, 31
	v_lshl_add_u64 v[36:37], s[38:39], 0, v[66:67]
	v_lshl_add_u64 v[36:37], v[36:37], 2, s[14:15]
	global_load_dword v36, v[36:37], off offset:240
	s_cmp_lt_i32 s50, 3
	s_mov_b64 s[18:19], -1
	s_cbranch_scc0 .LBB0_392

.LBB0_399:
	s_or_b64 exec, exec, s[12:13]
	ds_write_b32 v99, v35 offset:7920
	v_add_u32_e32 v35, 62, v34
	v_cmp_gt_i32_e32 vcc, s17, v35
	s_and_b64 s[12:13], s[4:5], vcc
	v_mov_b32_e32 v34, 0
	s_and_saveexec_b64 s[4:5], s[12:13]
	s_cbranch_execz .LBB0_411
	s_waitcnt vmcnt(0)
	v_mov_b32_e32 v32, v231
	s_and_b64 vcc, exec, s[2:3]
	s_cbranch_vccnz .LBB0_403
	s_ashr_i32 s39, s38, 31
	v_lshl_add_u64 v[34:35], s[38:39], 0, v[66:67]
	v_lshl_add_u64 v[34:35], v[34:35], 2, s[14:15]
	global_load_dword v33, v[34:35], off offset:248
	s_cmp_lt_i32 s50, 3
	s_mov_b64 s[2:3], -1
	s_cbranch_scc0 .LBB0_404

.LBB0_434:
	s_mul_i32 s2, s17, 0x50
	s_mul_hi_u32 s3, s16, 0x50
	s_add_i32 s3, s3, s2
	s_mul_i32 s2, s16, 0x50
	s_add_u32 s30, s0, s2
	s_addc_u32 s31, s1, s3
	s_load_dword s2, s[30:31], 0x150
	s_load_dword s40, s[30:31], 0x160
	s_load_dword s4, s[30:31], 0x168
	s_load_dwordx4 s[16:19], s[30:31], 0x140
	s_load_dwordx4 s[12:15], s[30:31], 0x120
	s_load_dwordx2 s[36:37], s[30:31], 0x130
	s_waitcnt lgkmcnt(0)
	s_ashr_i32 s3, s2, 31
	s_lshr_b32 s3, s3, 27
	s_add_i32 s2, s2, s3
	s_ashr_i32 s2, s2, 5
	s_abs_i32 s3, s2
	v_cvt_f32_u32_e32 v2, s3
	s_sub_i32 s34, 0, s3
	s_sub_i32 s4, s43, s4
	s_abs_i32 s5, s4
	v_rcp_iflag_f32_e32 v2, v2
	s_xor_b32 s19, s4, s2
	s_ashr_i32 s19, s19, 31
	v_mov_b32_e32 v3, s13
	v_mul_f32_e32 v2, 0x4f7ffffe, v2
	v_cvt_u32_f32_e32 v2, v2
	s_nop 0
	v_readfirstlane_b32 s35, v2
	s_mul_i32 s34, s34, s35
	s_mul_hi_u32 s34, s35, s34
	s_add_i32 s35, s35, s34
	s_mul_hi_u32 s34, s5, s35
	s_mul_i32 s35, s34, s3
	s_sub_i32 s5, s5, s35
	s_add_i32 s38, s34, 1
	s_sub_i32 s35, s5, s3
	s_cmp_ge_u32 s5, s3
	s_cselect_b32 s34, s38, s34
	s_cselect_b32 s5, s35, s5
	s_add_i32 s35, s34, 1
	s_cmp_ge_u32 s5, s3
	s_cselect_b32 s3, s35, s34
	s_xor_b32 s3, s3, s19
	s_sub_i32 s3, s3, s19
	s_mul_i32 s2, s3, s2
	s_sub_i32 s39, s4, s2
	s_lshl_b32 s38, s39, 5
	s_lshl_b32 s34, s3, 6
	v_or_b32_e32 v4, s38, v89
	v_mov_b32_e32 v2, s12
	v_ashrrev_i32_e32 v5, 31, v4
	s_cmp_lg_u64 s[14:15], 0
	v_cmp_gt_i32_e64 s[4:5], s18, v4
	v_lshl_add_u64 v[2:3], v[4:5], 2, v[2:3]
	s_cselect_b64 s[2:3], -1, 0
	v_add_u32_e32 v4, s34, v66
	v_cmp_gt_i32_e32 vcc, s17, v4
	v_cndmask_b32_e64 v8, 0, 1, s[2:3]
	s_and_b64 s[18:19], s[4:5], vcc
	v_mov_b32_e32 v5, 0
	v_cmp_ne_u32_e64 s[2:3], 1, v8
	v_add_u32_e32 v232, 0, v4
	v_cmp_gt_i32_e32 vcc, s17, v232
	s_nop 0
	s_and_b64 s[94:95], s[4:5], vcc
	s_and_saveexec_b64 s[96:97], s[94:95]
	s_cbranch_execz .Lcvpf1_0
	v_mad_i64_i32 v[234:235], s[98:99], s16, v232, 0
	v_lshl_add_u64 v[234:235], v[234:235], 2, v[2:3]
	global_load_dword v200, v[234:235], off
.Lcvpf1_0:
	s_or_b64 exec, exec, s[96:97]
	v_add_u32_e32 v232, 2, v4
	v_cmp_gt_i32_e32 vcc, s17, v232
	s_nop 0
	s_and_b64 s[94:95], s[4:5], vcc
	s_and_saveexec_b64 s[96:97], s[94:95]
	s_cbranch_execz .Lcvpf1_1
	v_mad_i64_i32 v[234:235], s[98:99], s16, v232, 0
	v_lshl_add_u64 v[234:235], v[234:235], 2, v[2:3]
	global_load_dword v201, v[234:235], off
.Lcvpf1_1:
	s_or_b64 exec, exec, s[96:97]
	v_add_u32_e32 v232, 4, v4
	v_cmp_gt_i32_e32 vcc, s17, v232
	s_nop 0
	s_and_b64 s[94:95], s[4:5], vcc
	s_and_saveexec_b64 s[96:97], s[94:95]
	s_cbranch_execz .Lcvpf1_2
	v_mad_i64_i32 v[234:235], s[98:99], s16, v232, 0
	v_lshl_add_u64 v[234:235], v[234:235], 2, v[2:3]
	global_load_dword v202, v[234:235], off
.Lcvpf1_2:
	s_or_b64 exec, exec, s[96:97]
	v_add_u32_e32 v232, 6, v4
	v_cmp_gt_i32_e32 vcc, s17, v232
	s_nop 0
	s_and_b64 s[94:95], s[4:5], vcc
	s_and_saveexec_b64 s[96:97], s[94:95]
	s_cbranch_execz .Lcvpf1_3
	v_mad_i64_i32 v[234:235], s[98:99], s16, v232, 0
	v_lshl_add_u64 v[234:235], v[234:235], 2, v[2:3]
	global_load_dword v203, v[234:235], off
.Lcvpf1_3:
	s_or_b64 exec, exec, s[96:97]
	v_add_u32_e32 v232, 8, v4
	v_cmp_gt_i32_e32 vcc, s17, v232
	s_nop 0
	s_and_b64 s[94:95], s[4:5], vcc
	s_and_saveexec_b64 s[96:97], s[94:95]
	s_cbranch_execz .Lcvpf1_4
	v_mad_i64_i32 v[234:235], s[98:99], s16, v232, 0
	v_lshl_add_u64 v[234:235], v[234:235], 2, v[2:3]
	global_load_dword v204, v[234:235], off
.Lcvpf1_4:
	s_or_b64 exec, exec, s[96:97]
	v_add_u32_e32 v232, 10, v4
	v_cmp_gt_i32_e32 vcc, s17, v232
	s_nop 0
	s_and_b64 s[94:95], s[4:5], vcc
	s_and_saveexec_b64 s[96:97], s[94:95]
	s_cbranch_execz .Lcvpf1_5
	v_mad_i64_i32 v[234:235], s[98:99], s16, v232, 0
	v_lshl_add_u64 v[234:235], v[234:235], 2, v[2:3]
	global_load_dword v205, v[234:235], off
.Lcvpf1_5:
	s_or_b64 exec, exec, s[96:97]
	v_add_u32_e32 v232, 12, v4
	v_cmp_gt_i32_e32 vcc, s17, v232
	s_nop 0
	s_and_b64 s[94:95], s[4:5], vcc
	s_and_saveexec_b64 s[96:97], s[94:95]
	s_cbranch_execz .Lcvpf1_6
	v_mad_i64_i32 v[234:235], s[98:99], s16, v232, 0
	v_lshl_add_u64 v[234:235], v[234:235], 2, v[2:3]
	global_load_dword v206, v[234:235], off
.Lcvpf1_6:
	s_or_b64 exec, exec, s[96:97]
	v_add_u32_e32 v232, 14, v4
	v_cmp_gt_i32_e32 vcc, s17, v232
	s_nop 0
	s_and_b64 s[94:95], s[4:5], vcc
	s_and_saveexec_b64 s[96:97], s[94:95]
	s_cbranch_execz .Lcvpf1_7
	v_mad_i64_i32 v[234:235], s[98:99], s16, v232, 0
	v_lshl_add_u64 v[234:235], v[234:235], 2, v[2:3]
	global_load_dword v207, v[234:235], off
.Lcvpf1_7:
	s_or_b64 exec, exec, s[96:97]
	v_add_u32_e32 v232, 16, v4
	v_cmp_gt_i32_e32 vcc, s17, v232
	s_nop 0
	s_and_b64 s[94:95], s[4:5], vcc
	s_and_saveexec_b64 s[96:97], s[94:95]
	s_cbranch_execz .Lcvpf1_8
	v_mad_i64_i32 v[234:235], s[98:99], s16, v232, 0
	v_lshl_add_u64 v[234:235], v[234:235], 2, v[2:3]
	global_load_dword v208, v[234:235], off
.Lcvpf1_8:
	s_or_b64 exec, exec, s[96:97]
	v_add_u32_e32 v232, 18, v4
	v_cmp_gt_i32_e32 vcc, s17, v232
	s_nop 0
	s_and_b64 s[94:95], s[4:5], vcc
	s_and_saveexec_b64 s[96:97], s[94:95]
	s_cbranch_execz .Lcvpf1_9
	v_mad_i64_i32 v[234:235], s[98:99], s16, v232, 0
	v_lshl_add_u64 v[234:235], v[234:235], 2, v[2:3]
	global_load_dword v209, v[234:235], off
.Lcvpf1_9:
	s_or_b64 exec, exec, s[96:97]
	v_add_u32_e32 v232, 20, v4
	v_cmp_gt_i32_e32 vcc, s17, v232
	s_nop 0
	s_and_b64 s[94:95], s[4:5], vcc
	s_and_saveexec_b64 s[96:97], s[94:95]
	s_cbranch_execz .Lcvpf1_10
	v_mad_i64_i32 v[234:235], s[98:99], s16, v232, 0
	v_lshl_add_u64 v[234:235], v[234:235], 2, v[2:3]
	global_load_dword v210, v[234:235], off
.Lcvpf1_10:
	s_or_b64 exec, exec, s[96:97]
	v_add_u32_e32 v232, 22, v4
	v_cmp_gt_i32_e32 vcc, s17, v232
	s_nop 0
	s_and_b64 s[94:95], s[4:5], vcc
	s_and_saveexec_b64 s[96:97], s[94:95]
	s_cbranch_execz .Lcvpf1_11
	v_mad_i64_i32 v[234:235], s[98:99], s16, v232, 0
	v_lshl_add_u64 v[234:235], v[234:235], 2, v[2:3]
	global_load_dword v211, v[234:235], off
.Lcvpf1_11:
	s_or_b64 exec, exec, s[96:97]
	v_add_u32_e32 v232, 24, v4
	v_cmp_gt_i32_e32 vcc, s17, v232
	s_nop 0
	s_and_b64 s[94:95], s[4:5], vcc
	s_and_saveexec_b64 s[96:97], s[94:95]
	s_cbranch_execz .Lcvpf1_12
	v_mad_i64_i32 v[234:235], s[98:99], s16, v232, 0
	v_lshl_add_u64 v[234:235], v[234:235], 2, v[2:3]
	global_load_dword v212, v[234:235], off
.Lcvpf1_12:
	s_or_b64 exec, exec, s[96:97]
	v_add_u32_e32 v232, 26, v4
	v_cmp_gt_i32_e32 vcc, s17, v232
	s_nop 0
	s_and_b64 s[94:95], s[4:5], vcc
	s_and_saveexec_b64 s[96:97], s[94:95]
	s_cbranch_execz .Lcvpf1_13
	v_mad_i64_i32 v[234:235], s[98:99], s16, v232, 0
	v_lshl_add_u64 v[234:235], v[234:235], 2, v[2:3]
	global_load_dword v213, v[234:235], off
.Lcvpf1_13:
	s_or_b64 exec, exec, s[96:97]
	v_add_u32_e32 v232, 28, v4
	v_cmp_gt_i32_e32 vcc, s17, v232
	s_nop 0
	s_and_b64 s[94:95], s[4:5], vcc
	s_and_saveexec_b64 s[96:97], s[94:95]
	s_cbranch_execz .Lcvpf1_14
	v_mad_i64_i32 v[234:235], s[98:99], s16, v232, 0
	v_lshl_add_u64 v[234:235], v[234:235], 2, v[2:3]
	global_load_dword v214, v[234:235], off
.Lcvpf1_14:
	s_or_b64 exec, exec, s[96:97]
	v_add_u32_e32 v232, 30, v4
	v_cmp_gt_i32_e32 vcc, s17, v232
	s_nop 0
	s_and_b64 s[94:95], s[4:5], vcc
	s_and_saveexec_b64 s[96:97], s[94:95]
	s_cbranch_execz .Lcvpf1_15
	v_mad_i64_i32 v[234:235], s[98:99], s16, v232, 0
	v_lshl_add_u64 v[234:235], v[234:235], 2, v[2:3]
	global_load_dword v215, v[234:235], off
.Lcvpf1_15:
	s_or_b64 exec, exec, s[96:97]
	v_add_u32_e32 v232, 32, v4
	v_cmp_gt_i32_e32 vcc, s17, v232
	s_nop 0
	s_and_b64 s[94:95], s[4:5], vcc
	s_and_saveexec_b64 s[96:97], s[94:95]
	s_cbranch_execz .Lcvpf1_16
	v_mad_i64_i32 v[234:235], s[98:99], s16, v232, 0
	v_lshl_add_u64 v[234:235], v[234:235], 2, v[2:3]
	global_load_dword v216, v[234:235], off
.Lcvpf1_16:
	s_or_b64 exec, exec, s[96:97]
	v_add_u32_e32 v232, 34, v4
	v_cmp_gt_i32_e32 vcc, s17, v232
	s_nop 0
	s_and_b64 s[94:95], s[4:5], vcc
	s_and_saveexec_b64 s[96:97], s[94:95]
	s_cbranch_execz .Lcvpf1_17
	v_mad_i64_i32 v[234:235], s[98:99], s16, v232, 0
	v_lshl_add_u64 v[234:235], v[234:235], 2, v[2:3]
	global_load_dword v217, v[234:235], off
.Lcvpf1_17:
	s_or_b64 exec, exec, s[96:97]
	v_add_u32_e32 v232, 36, v4
	v_cmp_gt_i32_e32 vcc, s17, v232
	s_nop 0
	s_and_b64 s[94:95], s[4:5], vcc
	s_and_saveexec_b64 s[96:97], s[94:95]
	s_cbranch_execz .Lcvpf1_18
	v_mad_i64_i32 v[234:235], s[98:99], s16, v232, 0
	v_lshl_add_u64 v[234:235], v[234:235], 2, v[2:3]
	global_load_dword v218, v[234:235], off
.Lcvpf1_18:
	s_or_b64 exec, exec, s[96:97]
	v_add_u32_e32 v232, 38, v4
	v_cmp_gt_i32_e32 vcc, s17, v232
	s_nop 0
	s_and_b64 s[94:95], s[4:5], vcc
	s_and_saveexec_b64 s[96:97], s[94:95]
	s_cbranch_execz .Lcvpf1_19
	v_mad_i64_i32 v[234:235], s[98:99], s16, v232, 0
	v_lshl_add_u64 v[234:235], v[234:235], 2, v[2:3]
	global_load_dword v219, v[234:235], off
.Lcvpf1_19:
	s_or_b64 exec, exec, s[96:97]
	v_add_u32_e32 v232, 40, v4
	v_cmp_gt_i32_e32 vcc, s17, v232
	s_nop 0
	s_and_b64 s[94:95], s[4:5], vcc
	s_and_saveexec_b64 s[96:97], s[94:95]
	s_cbranch_execz .Lcvpf1_20
	v_mad_i64_i32 v[234:235], s[98:99], s16, v232, 0
	v_lshl_add_u64 v[234:235], v[234:235], 2, v[2:3]
	global_load_dword v220, v[234:235], off
.Lcvpf1_20:
	s_or_b64 exec, exec, s[96:97]
	v_add_u32_e32 v232, 42, v4
	v_cmp_gt_i32_e32 vcc, s17, v232
	s_nop 0
	s_and_b64 s[94:95], s[4:5], vcc
	s_and_saveexec_b64 s[96:97], s[94:95]
	s_cbranch_execz .Lcvpf1_21
	v_mad_i64_i32 v[234:235], s[98:99], s16, v232, 0
	v_lshl_add_u64 v[234:235], v[234:235], 2, v[2:3]
	global_load_dword v221, v[234:235], off
.Lcvpf1_21:
	s_or_b64 exec, exec, s[96:97]
	v_add_u32_e32 v232, 44, v4
	v_cmp_gt_i32_e32 vcc, s17, v232
	s_nop 0
	s_and_b64 s[94:95], s[4:5], vcc
	s_and_saveexec_b64 s[96:97], s[94:95]
	s_cbranch_execz .Lcvpf1_22
	v_mad_i64_i32 v[234:235], s[98:99], s16, v232, 0
	v_lshl_add_u64 v[234:235], v[234:235], 2, v[2:3]
	global_load_dword v222, v[234:235], off
.Lcvpf1_22:
	s_or_b64 exec, exec, s[96:97]
	v_add_u32_e32 v232, 46, v4
	v_cmp_gt_i32_e32 vcc, s17, v232
	s_nop 0
	s_and_b64 s[94:95], s[4:5], vcc
	s_and_saveexec_b64 s[96:97], s[94:95]
	s_cbranch_execz .Lcvpf1_23
	v_mad_i64_i32 v[234:235], s[98:99], s16, v232, 0
	v_lshl_add_u64 v[234:235], v[234:235], 2, v[2:3]
	global_load_dword v223, v[234:235], off
.Lcvpf1_23:
	s_or_b64 exec, exec, s[96:97]
	v_add_u32_e32 v232, 48, v4
	v_cmp_gt_i32_e32 vcc, s17, v232
	s_nop 0
	s_and_b64 s[94:95], s[4:5], vcc
	s_and_saveexec_b64 s[96:97], s[94:95]
	s_cbranch_execz .Lcvpf1_24
	v_mad_i64_i32 v[234:235], s[98:99], s16, v232, 0
	v_lshl_add_u64 v[234:235], v[234:235], 2, v[2:3]
	global_load_dword v224, v[234:235], off
.Lcvpf1_24:
	s_or_b64 exec, exec, s[96:97]
	v_add_u32_e32 v232, 50, v4
	v_cmp_gt_i32_e32 vcc, s17, v232
	s_nop 0
	s_and_b64 s[94:95], s[4:5], vcc
	s_and_saveexec_b64 s[96:97], s[94:95]
	s_cbranch_execz .Lcvpf1_25
	v_mad_i64_i32 v[234:235], s[98:99], s16, v232, 0
	v_lshl_add_u64 v[234:235], v[234:235], 2, v[2:3]
	global_load_dword v225, v[234:235], off
.Lcvpf1_25:
	s_or_b64 exec, exec, s[96:97]
	v_add_u32_e32 v232, 52, v4
	v_cmp_gt_i32_e32 vcc, s17, v232
	s_nop 0
	s_and_b64 s[94:95], s[4:5], vcc
	s_and_saveexec_b64 s[96:97], s[94:95]
	s_cbranch_execz .Lcvpf1_26
	v_mad_i64_i32 v[234:235], s[98:99], s16, v232, 0
	v_lshl_add_u64 v[234:235], v[234:235], 2, v[2:3]
	global_load_dword v226, v[234:235], off
.Lcvpf1_26:
	s_or_b64 exec, exec, s[96:97]
	v_add_u32_e32 v232, 54, v4
	v_cmp_gt_i32_e32 vcc, s17, v232
	s_nop 0
	s_and_b64 s[94:95], s[4:5], vcc
	s_and_saveexec_b64 s[96:97], s[94:95]
	s_cbranch_execz .Lcvpf1_27
	v_mad_i64_i32 v[234:235], s[98:99], s16, v232, 0
	v_lshl_add_u64 v[234:235], v[234:235], 2, v[2:3]
	global_load_dword v227, v[234:235], off
.Lcvpf1_27:
	s_or_b64 exec, exec, s[96:97]
	v_add_u32_e32 v232, 56, v4
	v_cmp_gt_i32_e32 vcc, s17, v232
	s_nop 0
	s_and_b64 s[94:95], s[4:5], vcc
	s_and_saveexec_b64 s[96:97], s[94:95]
	s_cbranch_execz .Lcvpf1_28
	v_mad_i64_i32 v[234:235], s[98:99], s16, v232, 0
	v_lshl_add_u64 v[234:235], v[234:235], 2, v[2:3]
	global_load_dword v228, v[234:235], off
.Lcvpf1_28:
	s_or_b64 exec, exec, s[96:97]
	v_add_u32_e32 v232, 58, v4
	v_cmp_gt_i32_e32 vcc, s17, v232
	s_nop 0
	s_and_b64 s[94:95], s[4:5], vcc
	s_and_saveexec_b64 s[96:97], s[94:95]
	s_cbranch_execz .Lcvpf1_29
	v_mad_i64_i32 v[234:235], s[98:99], s16, v232, 0
	v_lshl_add_u64 v[234:235], v[234:235], 2, v[2:3]
	global_load_dword v229, v[234:235], off
.Lcvpf1_29:
	s_or_b64 exec, exec, s[96:97]
	v_add_u32_e32 v232, 60, v4
	v_cmp_gt_i32_e32 vcc, s17, v232
	s_nop 0
	s_and_b64 s[94:95], s[4:5], vcc
	s_and_saveexec_b64 s[96:97], s[94:95]
	s_cbranch_execz .Lcvpf1_30
	v_mad_i64_i32 v[234:235], s[98:99], s16, v232, 0
	v_lshl_add_u64 v[234:235], v[234:235], 2, v[2:3]
	global_load_dword v230, v[234:235], off
.Lcvpf1_30:
	s_or_b64 exec, exec, s[96:97]
	v_add_u32_e32 v232, 62, v4
	v_cmp_gt_i32_e32 vcc, s17, v232
	s_nop 0
	s_and_b64 s[94:95], s[4:5], vcc
	s_and_saveexec_b64 s[96:97], s[94:95]
	s_cbranch_execz .Lcvpf1_31
	v_mad_i64_i32 v[234:235], s[98:99], s16, v232, 0
	v_lshl_add_u64 v[234:235], v[234:235], 2, v[2:3]
	global_load_dword v231, v[234:235], off
.Lcvpf1_31:
	s_or_b64 exec, exec, s[96:97]
	s_and_saveexec_b64 s[12:13], s[18:19]
	s_cbranch_execz .LBB0_446
	s_waitcnt vmcnt(0)
	v_mov_b32_e32 v8, v200
	s_and_b64 vcc, exec, s[2:3]
	v_ashrrev_i32_e32 v5, 31, v4
	s_cbranch_vccnz .LBB0_438
	v_lshl_add_u64 v[10:11], v[4:5], 2, s[14:15]
	global_load_dword v9, v[10:11], off
	s_cmp_lt_i32 s40, 3
	s_mov_b64 s[18:19], -1
	s_cbranch_scc0 .LBB0_439

.LBB0_446:
	s_or_b64 exec, exec, s[12:13]
	v_add_u32_e32 v8, 2, v4
	v_cmp_gt_i32_e32 vcc, s17, v8
	ds_write_b32 v7, v5
	s_and_b64 s[18:19], s[4:5], vcc
	v_mov_b32_e32 v5, 0
	s_and_saveexec_b64 s[12:13], s[18:19]
	s_cbranch_execz .LBB0_458
	s_waitcnt vmcnt(0)
	v_mov_b32_e32 v5, v201
	s_and_b64 vcc, exec, s[2:3]
	s_cbranch_vccnz .LBB0_450
	s_ashr_i32 s35, s34, 31
	v_lshl_add_u64 v[8:9], s[34:35], 0, v[66:67]
	v_lshl_add_u64 v[8:9], v[8:9], 2, s[14:15]
	global_load_dword v8, v[8:9], off offset:8
	s_cmp_lt_i32 s40, 3
	s_mov_b64 s[18:19], -1
	s_cbranch_scc0 .LBB0_451

.LBB0_458:
	s_or_b64 exec, exec, s[12:13]
	v_add_u32_e32 v8, 4, v4
	v_cmp_gt_i32_e32 vcc, s17, v8
	ds_write_b32 v7, v5 offset:264
	s_and_b64 s[18:19], s[4:5], vcc
	v_mov_b32_e32 v5, 0
	s_and_saveexec_b64 s[12:13], s[18:19]
	s_cbranch_execz .LBB0_470
	s_waitcnt vmcnt(0)
	v_mov_b32_e32 v5, v202
	s_and_b64 vcc, exec, s[2:3]
	s_cbranch_vccnz .LBB0_462
	s_ashr_i32 s35, s34, 31
	v_lshl_add_u64 v[8:9], s[34:35], 0, v[66:67]
	v_lshl_add_u64 v[8:9], v[8:9], 2, s[14:15]
	global_load_dword v8, v[8:9], off offset:16
	s_cmp_lt_i32 s40, 3
	s_mov_b64 s[18:19], -1
	s_cbranch_scc0 .LBB0_463

.LBB0_470:
	s_or_b64 exec, exec, s[12:13]
	v_add_u32_e32 v8, 6, v4
	v_cmp_gt_i32_e32 vcc, s17, v8
	ds_write_b32 v7, v5 offset:528
	s_and_b64 s[18:19], s[4:5], vcc
	v_mov_b32_e32 v5, 0
	s_and_saveexec_b64 s[12:13], s[18:19]
	s_cbranch_execz .LBB0_482
	s_waitcnt vmcnt(0)
	v_mov_b32_e32 v5, v203
	s_and_b64 vcc, exec, s[2:3]
	s_cbranch_vccnz .LBB0_474
	s_ashr_i32 s35, s34, 31
	v_lshl_add_u64 v[8:9], s[34:35], 0, v[66:67]
	v_lshl_add_u64 v[8:9], v[8:9], 2, s[14:15]
	global_load_dword v8, v[8:9], off offset:24
	s_cmp_lt_i32 s40, 3
	s_mov_b64 s[18:19], -1
	s_cbranch_scc0 .LBB0_475

.LBB0_482:
	s_or_b64 exec, exec, s[12:13]
	v_add_u32_e32 v8, 8, v4
	v_cmp_gt_i32_e32 vcc, s17, v8
	ds_write_b32 v7, v5 offset:792
	s_and_b64 s[18:19], s[4:5], vcc
	v_mov_b32_e32 v5, 0
	s_and_saveexec_b64 s[12:13], s[18:19]
	s_cbranch_execz .LBB0_494
	s_waitcnt vmcnt(0)
	v_mov_b32_e32 v5, v204
	s_and_b64 vcc, exec, s[2:3]
	s_cbranch_vccnz .LBB0_486
	s_ashr_i32 s35, s34, 31
	v_lshl_add_u64 v[8:9], s[34:35], 0, v[66:67]
	v_lshl_add_u64 v[8:9], v[8:9], 2, s[14:15]
	global_load_dword v8, v[8:9], off offset:32
	s_cmp_lt_i32 s40, 3
	s_mov_b64 s[18:19], -1
	s_cbranch_scc0 .LBB0_487

.LBB0_494:
	s_or_b64 exec, exec, s[12:13]
	v_add_u32_e32 v8, 10, v4
	v_cmp_gt_i32_e32 vcc, s17, v8
	ds_write_b32 v7, v5 offset:1056
	s_and_b64 s[18:19], s[4:5], vcc
	v_mov_b32_e32 v5, 0
	s_and_saveexec_b64 s[12:13], s[18:19]
	s_cbranch_execz .LBB0_506
	s_waitcnt vmcnt(0)
	v_mov_b32_e32 v5, v205
	s_and_b64 vcc, exec, s[2:3]
	s_cbranch_vccnz .LBB0_498
	s_ashr_i32 s35, s34, 31
	v_lshl_add_u64 v[8:9], s[34:35], 0, v[66:67]
	v_lshl_add_u64 v[8:9], v[8:9], 2, s[14:15]
	global_load_dword v8, v[8:9], off offset:40
	s_cmp_lt_i32 s40, 3
	s_mov_b64 s[18:19], -1
	s_cbranch_scc0 .LBB0_499

.LBB0_506:
	s_or_b64 exec, exec, s[12:13]
	v_add_u32_e32 v8, 12, v4
	v_cmp_gt_i32_e32 vcc, s17, v8
	ds_write_b32 v7, v5 offset:1320
	s_and_b64 s[18:19], s[4:5], vcc
	v_mov_b32_e32 v5, 0
	s_and_saveexec_b64 s[12:13], s[18:19]
	s_cbranch_execz .LBB0_518
	s_waitcnt vmcnt(0)
	v_mov_b32_e32 v5, v206
	s_and_b64 vcc, exec, s[2:3]
	s_cbranch_vccnz .LBB0_510
	s_ashr_i32 s35, s34, 31
	v_lshl_add_u64 v[8:9], s[34:35], 0, v[66:67]
	v_lshl_add_u64 v[8:9], v[8:9], 2, s[14:15]
	global_load_dword v8, v[8:9], off offset:48
	s_cmp_lt_i32 s40, 3
	s_mov_b64 s[18:19], -1
	s_cbranch_scc0 .LBB0_511

.LBB0_518:
	s_or_b64 exec, exec, s[12:13]
	v_add_u32_e32 v8, 14, v4
	v_cmp_gt_i32_e32 vcc, s17, v8
	ds_write_b32 v7, v5 offset:1584
	s_and_b64 s[18:19], s[4:5], vcc
	v_mov_b32_e32 v5, 0
	s_and_saveexec_b64 s[12:13], s[18:19]
	s_cbranch_execz .LBB0_530
	s_waitcnt vmcnt(0)
	v_mov_b32_e32 v5, v207
	s_and_b64 vcc, exec, s[2:3]
	s_cbranch_vccnz .LBB0_522
	s_ashr_i32 s35, s34, 31
	v_lshl_add_u64 v[8:9], s[34:35], 0, v[66:67]
	v_lshl_add_u64 v[8:9], v[8:9], 2, s[14:15]
	global_load_dword v8, v[8:9], off offset:56
	s_cmp_lt_i32 s40, 3
	s_mov_b64 s[18:19], -1
	s_cbranch_scc0 .LBB0_523

.LBB0_530:
	s_or_b64 exec, exec, s[12:13]
	v_add_u32_e32 v8, 16, v4
	v_cmp_gt_i32_e32 vcc, s17, v8
	ds_write_b32 v7, v5 offset:1848
	s_and_b64 s[18:19], s[4:5], vcc
	v_mov_b32_e32 v5, 0
	s_and_saveexec_b64 s[12:13], s[18:19]
	s_cbranch_execz .LBB0_542
	s_waitcnt vmcnt(0)
	v_mov_b32_e32 v5, v208
	s_and_b64 vcc, exec, s[2:3]
	s_cbranch_vccnz .LBB0_534
	s_ashr_i32 s35, s34, 31
	v_lshl_add_u64 v[8:9], s[34:35], 0, v[66:67]
	v_lshl_add_u64 v[8:9], v[8:9], 2, s[14:15]
	global_load_dword v8, v[8:9], off offset:64
	s_cmp_lt_i32 s40, 3
	s_mov_b64 s[18:19], -1
	s_cbranch_scc0 .LBB0_535

.LBB0_542:
	s_or_b64 exec, exec, s[12:13]
	v_add_u32_e32 v8, 18, v4
	v_cmp_gt_i32_e32 vcc, s17, v8
	ds_write_b32 v7, v5 offset:2112
	s_and_b64 s[18:19], s[4:5], vcc
	v_mov_b32_e32 v5, 0
	s_and_saveexec_b64 s[12:13], s[18:19]
	s_cbranch_execz .LBB0_554
	s_waitcnt vmcnt(0)
	v_mov_b32_e32 v5, v209
	s_and_b64 vcc, exec, s[2:3]
	s_cbranch_vccnz .LBB0_546
	s_ashr_i32 s35, s34, 31
	v_lshl_add_u64 v[8:9], s[34:35], 0, v[66:67]
	v_lshl_add_u64 v[8:9], v[8:9], 2, s[14:15]
	global_load_dword v8, v[8:9], off offset:72
	s_cmp_lt_i32 s40, 3
	s_mov_b64 s[18:19], -1
	s_cbranch_scc0 .LBB0_547

.LBB0_554:
	s_or_b64 exec, exec, s[12:13]
	v_add_u32_e32 v8, 20, v4
	v_cmp_gt_i32_e32 vcc, s17, v8
	ds_write_b32 v7, v5 offset:2376
	s_and_b64 s[18:19], s[4:5], vcc
	v_mov_b32_e32 v5, 0
	s_and_saveexec_b64 s[12:13], s[18:19]
	s_cbranch_execz .LBB0_566
	s_waitcnt vmcnt(0)
	v_mov_b32_e32 v5, v210
	s_and_b64 vcc, exec, s[2:3]
	s_cbranch_vccnz .LBB0_558
	s_ashr_i32 s35, s34, 31
	v_lshl_add_u64 v[8:9], s[34:35], 0, v[66:67]
	v_lshl_add_u64 v[8:9], v[8:9], 2, s[14:15]
	global_load_dword v8, v[8:9], off offset:80
	s_cmp_lt_i32 s40, 3
	s_mov_b64 s[18:19], -1
	s_cbranch_scc0 .LBB0_559

.LBB0_566:
	s_or_b64 exec, exec, s[12:13]
	v_add_u32_e32 v8, 22, v4
	v_cmp_gt_i32_e32 vcc, s17, v8
	ds_write_b32 v7, v5 offset:2640
	s_and_b64 s[18:19], s[4:5], vcc
	v_mov_b32_e32 v5, 0
	s_and_saveexec_b64 s[12:13], s[18:19]
	s_cbranch_execz .LBB0_578
	s_waitcnt vmcnt(0)
	v_mov_b32_e32 v5, v211
	s_and_b64 vcc, exec, s[2:3]
	s_cbranch_vccnz .LBB0_570
	s_ashr_i32 s35, s34, 31
	v_lshl_add_u64 v[8:9], s[34:35], 0, v[66:67]
	v_lshl_add_u64 v[8:9], v[8:9], 2, s[14:15]
	global_load_dword v8, v[8:9], off offset:88
	s_cmp_lt_i32 s40, 3
	s_mov_b64 s[18:19], -1
	s_cbranch_scc0 .LBB0_571

.LBB0_578:
	s_or_b64 exec, exec, s[12:13]
	v_add_u32_e32 v8, 24, v4
	v_cmp_gt_i32_e32 vcc, s17, v8
	ds_write_b32 v7, v5 offset:2904
	s_and_b64 s[18:19], s[4:5], vcc
	v_mov_b32_e32 v5, 0
	s_and_saveexec_b64 s[12:13], s[18:19]
	s_cbranch_execz .LBB0_590
	s_waitcnt vmcnt(0)
	v_mov_b32_e32 v5, v212
	s_and_b64 vcc, exec, s[2:3]
	s_cbranch_vccnz .LBB0_582
	s_ashr_i32 s35, s34, 31
	v_lshl_add_u64 v[8:9], s[34:35], 0, v[66:67]
	v_lshl_add_u64 v[8:9], v[8:9], 2, s[14:15]
	global_load_dword v8, v[8:9], off offset:96
	s_cmp_lt_i32 s40, 3
	s_mov_b64 s[18:19], -1
	s_cbranch_scc0 .LBB0_583

.LBB0_590:
	s_or_b64 exec, exec, s[12:13]
	v_add_u32_e32 v8, 26, v4
	v_cmp_gt_i32_e32 vcc, s17, v8
	ds_write_b32 v7, v5 offset:3168
	s_and_b64 s[18:19], s[4:5], vcc
	v_mov_b32_e32 v5, 0
	s_and_saveexec_b64 s[12:13], s[18:19]
	s_cbranch_execz .LBB0_602
	s_waitcnt vmcnt(0)
	v_mov_b32_e32 v5, v213
	s_and_b64 vcc, exec, s[2:3]
	s_cbranch_vccnz .LBB0_594
	s_ashr_i32 s35, s34, 31
	v_lshl_add_u64 v[8:9], s[34:35], 0, v[66:67]
	v_lshl_add_u64 v[8:9], v[8:9], 2, s[14:15]
	global_load_dword v8, v[8:9], off offset:104
	s_cmp_lt_i32 s40, 3
	s_mov_b64 s[18:19], -1
	s_cbranch_scc0 .LBB0_595

.LBB0_602:
	s_or_b64 exec, exec, s[12:13]
	v_add_u32_e32 v8, 28, v4
	v_cmp_gt_i32_e32 vcc, s17, v8
	ds_write_b32 v7, v5 offset:3432
	s_and_b64 s[18:19], s[4:5], vcc
	v_mov_b32_e32 v5, 0
	s_and_saveexec_b64 s[12:13], s[18:19]
	s_cbranch_execz .LBB0_614
	s_waitcnt vmcnt(0)
	v_mov_b32_e32 v5, v214
	s_and_b64 vcc, exec, s[2:3]
	s_cbranch_vccnz .LBB0_606
	s_ashr_i32 s35, s34, 31
	v_lshl_add_u64 v[8:9], s[34:35], 0, v[66:67]
	v_lshl_add_u64 v[8:9], v[8:9], 2, s[14:15]
	global_load_dword v8, v[8:9], off offset:112
	s_cmp_lt_i32 s40, 3
	s_mov_b64 s[18:19], -1
	s_cbranch_scc0 .LBB0_607

.LBB0_614:
	s_or_b64 exec, exec, s[12:13]
	v_add_u32_e32 v8, 30, v4
	v_cmp_gt_i32_e32 vcc, s17, v8
	ds_write_b32 v7, v5 offset:3696
	s_and_b64 s[18:19], s[4:5], vcc
	v_mov_b32_e32 v5, 0
	s_and_saveexec_b64 s[12:13], s[18:19]
	s_cbranch_execz .LBB0_626
	s_waitcnt vmcnt(0)
	v_mov_b32_e32 v5, v215
	s_and_b64 vcc, exec, s[2:3]
	s_cbranch_vccnz .LBB0_618
	s_ashr_i32 s35, s34, 31
	v_lshl_add_u64 v[8:9], s[34:35], 0, v[66:67]
	v_lshl_add_u64 v[8:9], v[8:9], 2, s[14:15]
	global_load_dword v8, v[8:9], off offset:120
	s_cmp_lt_i32 s40, 3
	s_mov_b64 s[18:19], -1
	s_cbranch_scc0 .LBB0_619

.LBB0_626:
	s_or_b64 exec, exec, s[12:13]
	v_add_u32_e32 v8, 32, v4
	v_cmp_gt_i32_e32 vcc, s17, v8
	ds_write_b32 v7, v5 offset:3960
	s_and_b64 s[18:19], s[4:5], vcc
	v_mov_b32_e32 v5, 0
	s_and_saveexec_b64 s[12:13], s[18:19]
	s_cbranch_execz .LBB0_638
	s_waitcnt vmcnt(0)
	v_mov_b32_e32 v5, v216
	s_and_b64 vcc, exec, s[2:3]
	s_cbranch_vccnz .LBB0_630
	s_ashr_i32 s35, s34, 31
	v_lshl_add_u64 v[8:9], s[34:35], 0, v[66:67]
	v_lshl_add_u64 v[8:9], v[8:9], 2, s[14:15]
	global_load_dword v8, v[8:9], off offset:128
	s_cmp_lt_i32 s40, 3
	s_mov_b64 s[18:19], -1
	s_cbranch_scc0 .LBB0_631

.LBB0_638:
	s_or_b64 exec, exec, s[12:13]
	v_add_u32_e32 v8, 34, v4
	v_cmp_gt_i32_e32 vcc, s17, v8
	ds_write_b32 v7, v5 offset:4224
	s_and_b64 s[18:19], s[4:5], vcc
	v_mov_b32_e32 v5, 0
	s_and_saveexec_b64 s[12:13], s[18:19]
	s_cbranch_execz .LBB0_650
	s_waitcnt vmcnt(0)
	v_mov_b32_e32 v5, v217
	s_and_b64 vcc, exec, s[2:3]
	s_cbranch_vccnz .LBB0_642
	s_ashr_i32 s35, s34, 31
	v_lshl_add_u64 v[8:9], s[34:35], 0, v[66:67]
	v_lshl_add_u64 v[8:9], v[8:9], 2, s[14:15]
	global_load_dword v8, v[8:9], off offset:136
	s_cmp_lt_i32 s40, 3
	s_mov_b64 s[18:19], -1
	s_cbranch_scc0 .LBB0_643

.LBB0_650:
	s_or_b64 exec, exec, s[12:13]
	v_add_u32_e32 v8, 36, v4
	v_cmp_gt_i32_e32 vcc, s17, v8
	ds_write_b32 v7, v5 offset:4488
	s_and_b64 s[18:19], s[4:5], vcc
	v_mov_b32_e32 v5, 0
	s_and_saveexec_b64 s[12:13], s[18:19]
	s_cbranch_execz .LBB0_662
	s_waitcnt vmcnt(0)
	v_mov_b32_e32 v5, v218
	s_and_b64 vcc, exec, s[2:3]
	s_cbranch_vccnz .LBB0_654
	s_ashr_i32 s35, s34, 31
	v_lshl_add_u64 v[8:9], s[34:35], 0, v[66:67]
	v_lshl_add_u64 v[8:9], v[8:9], 2, s[14:15]
	global_load_dword v8, v[8:9], off offset:144
	s_cmp_lt_i32 s40, 3
	s_mov_b64 s[18:19], -1
	s_cbranch_scc0 .LBB0_655

.LBB0_662:
	s_or_b64 exec, exec, s[12:13]
	v_add_u32_e32 v8, 38, v4
	v_cmp_gt_i32_e32 vcc, s17, v8
	ds_write_b32 v7, v5 offset:4752
	s_and_b64 s[18:19], s[4:5], vcc
	v_mov_b32_e32 v5, 0
	s_and_saveexec_b64 s[12:13], s[18:19]
	s_cbranch_execz .LBB0_674
	s_waitcnt vmcnt(0)
	v_mov_b32_e32 v5, v219
	s_and_b64 vcc, exec, s[2:3]
	s_cbranch_vccnz .LBB0_666
	s_ashr_i32 s35, s34, 31
	v_lshl_add_u64 v[8:9], s[34:35], 0, v[66:67]
	v_lshl_add_u64 v[8:9], v[8:9], 2, s[14:15]
	global_load_dword v8, v[8:9], off offset:152
	s_cmp_lt_i32 s40, 3
	s_mov_b64 s[18:19], -1
	s_cbranch_scc0 .LBB0_667

.LBB0_674:
	s_or_b64 exec, exec, s[12:13]
	v_add_u32_e32 v8, 40, v4
	v_cmp_gt_i32_e32 vcc, s17, v8
	ds_write_b32 v7, v5 offset:5016
	s_and_b64 s[18:19], s[4:5], vcc
	v_mov_b32_e32 v5, 0
	s_and_saveexec_b64 s[12:13], s[18:19]
	s_cbranch_execz .LBB0_686
	s_waitcnt vmcnt(0)
	v_mov_b32_e32 v5, v220
	s_and_b64 vcc, exec, s[2:3]
	s_cbranch_vccnz .LBB0_678
	s_ashr_i32 s35, s34, 31
	v_lshl_add_u64 v[8:9], s[34:35], 0, v[66:67]
	v_lshl_add_u64 v[8:9], v[8:9], 2, s[14:15]
	global_load_dword v8, v[8:9], off offset:160
	s_cmp_lt_i32 s40, 3
	s_mov_b64 s[18:19], -1
	s_cbranch_scc0 .LBB0_679

.LBB0_686:
	s_or_b64 exec, exec, s[12:13]
	v_add_u32_e32 v8, 42, v4
	v_cmp_gt_i32_e32 vcc, s17, v8
	ds_write_b32 v7, v5 offset:5280
	s_and_b64 s[18:19], s[4:5], vcc
	v_mov_b32_e32 v5, 0
	s_and_saveexec_b64 s[12:13], s[18:19]
	s_cbranch_execz .LBB0_698
	s_waitcnt vmcnt(0)
	v_mov_b32_e32 v5, v221
	s_and_b64 vcc, exec, s[2:3]
	s_cbranch_vccnz .LBB0_690
	s_ashr_i32 s35, s34, 31
	v_lshl_add_u64 v[8:9], s[34:35], 0, v[66:67]
	v_lshl_add_u64 v[8:9], v[8:9], 2, s[14:15]
	global_load_dword v8, v[8:9], off offset:168
	s_cmp_lt_i32 s40, 3
	s_mov_b64 s[18:19], -1
	s_cbranch_scc0 .LBB0_691

.LBB0_698:
	s_or_b64 exec, exec, s[12:13]
	v_add_u32_e32 v8, 44, v4
	v_cmp_gt_i32_e32 vcc, s17, v8
	ds_write_b32 v7, v5 offset:5544
	s_and_b64 s[18:19], s[4:5], vcc
	v_mov_b32_e32 v5, 0
	s_and_saveexec_b64 s[12:13], s[18:19]
	s_cbranch_execz .LBB0_710
	s_waitcnt vmcnt(0)
	v_mov_b32_e32 v5, v222
	s_and_b64 vcc, exec, s[2:3]
	s_cbranch_vccnz .LBB0_702
	s_ashr_i32 s35, s34, 31
	v_lshl_add_u64 v[8:9], s[34:35], 0, v[66:67]
	v_lshl_add_u64 v[8:9], v[8:9], 2, s[14:15]
	global_load_dword v8, v[8:9], off offset:176
	s_cmp_lt_i32 s40, 3
	s_mov_b64 s[18:19], -1
	s_cbranch_scc0 .LBB0_703

.LBB0_710:
	s_or_b64 exec, exec, s[12:13]
	v_add_u32_e32 v8, 46, v4
	v_cmp_gt_i32_e32 vcc, s17, v8
	ds_write_b32 v7, v5 offset:5808
	s_and_b64 s[18:19], s[4:5], vcc
	v_mov_b32_e32 v5, 0
	s_and_saveexec_b64 s[12:13], s[18:19]
	s_cbranch_execz .LBB0_722
	s_waitcnt vmcnt(0)
	v_mov_b32_e32 v5, v223
	s_and_b64 vcc, exec, s[2:3]
	s_cbranch_vccnz .LBB0_714
	s_ashr_i32 s35, s34, 31
	v_lshl_add_u64 v[8:9], s[34:35], 0, v[66:67]
	v_lshl_add_u64 v[8:9], v[8:9], 2, s[14:15]
	global_load_dword v8, v[8:9], off offset:184
	s_cmp_lt_i32 s40, 3
	s_mov_b64 s[18:19], -1
	s_cbranch_scc0 .LBB0_715

.LBB0_722:
	s_or_b64 exec, exec, s[12:13]
	v_add_u32_e32 v8, 48, v4
	v_cmp_gt_i32_e32 vcc, s17, v8
	ds_write_b32 v7, v5 offset:6072
	s_and_b64 s[18:19], s[4:5], vcc
	v_mov_b32_e32 v5, 0
	s_and_saveexec_b64 s[12:13], s[18:19]
	s_cbranch_execz .LBB0_734
	s_waitcnt vmcnt(0)
	v_mov_b32_e32 v5, v224
	s_and_b64 vcc, exec, s[2:3]
	s_cbranch_vccnz .LBB0_726
	s_ashr_i32 s35, s34, 31
	v_lshl_add_u64 v[8:9], s[34:35], 0, v[66:67]
	v_lshl_add_u64 v[8:9], v[8:9], 2, s[14:15]
	global_load_dword v8, v[8:9], off offset:192
	s_cmp_lt_i32 s40, 3
	s_mov_b64 s[18:19], -1
	s_cbranch_scc0 .LBB0_727

.LBB0_734:
	s_or_b64 exec, exec, s[12:13]
	v_add_u32_e32 v8, 50, v4
	v_cmp_gt_i32_e32 vcc, s17, v8
	ds_write_b32 v7, v5 offset:6336
	s_and_b64 s[18:19], s[4:5], vcc
	v_mov_b32_e32 v5, 0
	s_and_saveexec_b64 s[12:13], s[18:19]
	s_cbranch_execz .LBB0_746
	s_waitcnt vmcnt(0)
	v_mov_b32_e32 v5, v225
	s_and_b64 vcc, exec, s[2:3]
	s_cbranch_vccnz .LBB0_738
	s_ashr_i32 s35, s34, 31
	v_lshl_add_u64 v[8:9], s[34:35], 0, v[66:67]
	v_lshl_add_u64 v[8:9], v[8:9], 2, s[14:15]
	global_load_dword v8, v[8:9], off offset:200
	s_cmp_lt_i32 s40, 3
	s_mov_b64 s[18:19], -1
	s_cbranch_scc0 .LBB0_739

.LBB0_746:
	s_or_b64 exec, exec, s[12:13]
	v_add_u32_e32 v8, 52, v4
	v_cmp_gt_i32_e32 vcc, s17, v8
	ds_write_b32 v7, v5 offset:6600
	s_and_b64 s[18:19], s[4:5], vcc
	v_mov_b32_e32 v5, 0
	s_and_saveexec_b64 s[12:13], s[18:19]
	s_cbranch_execz .LBB0_758
	s_waitcnt vmcnt(0)
	v_mov_b32_e32 v5, v226
	s_and_b64 vcc, exec, s[2:3]
	s_cbranch_vccnz .LBB0_750
	s_ashr_i32 s35, s34, 31
	v_lshl_add_u64 v[8:9], s[34:35], 0, v[66:67]
	v_lshl_add_u64 v[8:9], v[8:9], 2, s[14:15]
	global_load_dword v8, v[8:9], off offset:208
	s_cmp_lt_i32 s40, 3
	s_mov_b64 s[18:19], -1
	s_cbranch_scc0 .LBB0_751

.LBB0_758:
	s_or_b64 exec, exec, s[12:13]
	v_add_u32_e32 v8, 54, v4
	v_cmp_gt_i32_e32 vcc, s17, v8
	ds_write_b32 v7, v5 offset:6864
	s_and_b64 s[18:19], s[4:5], vcc
	v_mov_b32_e32 v5, 0
	s_and_saveexec_b64 s[12:13], s[18:19]
	s_cbranch_execz .LBB0_770
	s_waitcnt vmcnt(0)
	v_mov_b32_e32 v5, v227
	s_and_b64 vcc, exec, s[2:3]
	s_cbranch_vccnz .LBB0_762
	s_ashr_i32 s35, s34, 31
	v_lshl_add_u64 v[8:9], s[34:35], 0, v[66:67]
	v_lshl_add_u64 v[8:9], v[8:9], 2, s[14:15]
	global_load_dword v8, v[8:9], off offset:216
	s_cmp_lt_i32 s40, 3
	s_mov_b64 s[18:19], -1
	s_cbranch_scc0 .LBB0_763

.LBB0_770:
	s_or_b64 exec, exec, s[12:13]
	v_add_u32_e32 v8, 56, v4
	v_cmp_gt_i32_e32 vcc, s17, v8
	ds_write_b32 v7, v5 offset:7128
	s_and_b64 s[18:19], s[4:5], vcc
	v_mov_b32_e32 v5, 0
	s_and_saveexec_b64 s[12:13], s[18:19]
	s_cbranch_execz .LBB0_782
	s_waitcnt vmcnt(0)
	v_mov_b32_e32 v5, v228
	s_and_b64 vcc, exec, s[2:3]
	s_cbranch_vccnz .LBB0_774
	s_ashr_i32 s35, s34, 31
	v_lshl_add_u64 v[8:9], s[34:35], 0, v[66:67]
	v_lshl_add_u64 v[8:9], v[8:9], 2, s[14:15]
	global_load_dword v8, v[8:9], off offset:224
	s_cmp_lt_i32 s40, 3
	s_mov_b64 s[18:19], -1
	s_cbranch_scc0 .LBB0_775

.LBB0_782:
	s_or_b64 exec, exec, s[12:13]
	v_add_u32_e32 v8, 58, v4
	v_cmp_gt_i32_e32 vcc, s17, v8
	ds_write_b32 v7, v5 offset:7392
	s_and_b64 s[18:19], s[4:5], vcc
	v_mov_b32_e32 v5, 0
	s_and_saveexec_b64 s[12:13], s[18:19]
	s_cbranch_execz .LBB0_794
	s_waitcnt vmcnt(0)
	v_mov_b32_e32 v5, v229
	s_and_b64 vcc, exec, s[2:3]
	s_cbranch_vccnz .LBB0_786
	s_ashr_i32 s35, s34, 31
	v_lshl_add_u64 v[8:9], s[34:35], 0, v[66:67]
	v_lshl_add_u64 v[8:9], v[8:9], 2, s[14:15]
	global_load_dword v8, v[8:9], off offset:232
	s_cmp_lt_i32 s40, 3
	s_mov_b64 s[18:19], -1
	s_cbranch_scc0 .LBB0_787

.LBB0_794:
	s_or_b64 exec, exec, s[12:13]
	v_add_u32_e32 v8, 60, v4
	v_cmp_gt_i32_e32 vcc, s17, v8
	ds_write_b32 v7, v5 offset:7656
	s_and_b64 s[18:19], s[4:5], vcc
	v_mov_b32_e32 v5, 0
	s_and_saveexec_b64 s[12:13], s[18:19]
	s_cbranch_execz .LBB0_806
	s_waitcnt vmcnt(0)
	v_mov_b32_e32 v5, v230
	s_and_b64 vcc, exec, s[2:3]
	s_cbranch_vccnz .LBB0_798
	s_ashr_i32 s35, s34, 31
	v_lshl_add_u64 v[8:9], s[34:35], 0, v[66:67]
	v_lshl_add_u64 v[8:9], v[8:9], 2, s[14:15]
	global_load_dword v8, v[8:9], off offset:240
	s_cmp_lt_i32 s40, 3
	s_mov_b64 s[18:19], -1
	s_cbranch_scc0 .LBB0_799

.LBB0_806:
	s_or_b64 exec, exec, s[12:13]
	ds_write_b32 v7, v5 offset:7920
	v_add_u32_e32 v5, 62, v4
	v_cmp_gt_i32_e32 vcc, s17, v5
	s_and_b64 s[12:13], s[4:5], vcc
	v_mov_b32_e32 v4, 0
	s_and_saveexec_b64 s[4:5], s[12:13]
	s_cbranch_execz .LBB0_818
	s_waitcnt vmcnt(0)
	v_mov_b32_e32 v2, v231
	s_and_b64 vcc, exec, s[2:3]
	s_cbranch_vccnz .LBB0_810
	s_ashr_i32 s35, s34, 31
	v_lshl_add_u64 v[4:5], s[34:35], 0, v[66:67]
	v_lshl_add_u64 v[4:5], v[4:5], 2, s[14:15]
	global_load_dword v3, v[4:5], off offset:248
	s_cmp_lt_i32 s40, 3
	s_mov_b64 s[2:3], -1
	s_cbranch_scc0 .LBB0_811

	.amdhsa_kernel _Z8yoco_fwd4Args
		.amdhsa_group_segment_fixed_size 0
		.amdhsa_private_segment_fixed_size 0
		.amdhsa_kernarg_size 2240
		.amdhsa_user_sgpr_count 2
		.amdhsa_user_sgpr_dispatch_ptr 0
		.amdhsa_user_sgpr_queue_ptr 0
		.amdhsa_user_sgpr_kernarg_segment_ptr 1
		.amdhsa_user_sgpr_dispatch_id 0
		.amdhsa_user_sgpr_kernarg_preload_length 0
		.amdhsa_user_sgpr_kernarg_preload_offset 0
		.amdhsa_user_sgpr_private_segment_size 0
		.amdhsa_uses_dynamic_stack 0
		.amdhsa_enable_private_segment 0
		.amdhsa_system_sgpr_workgroup_id_x 1
		.amdhsa_system_sgpr_workgroup_id_y 0
		.amdhsa_system_sgpr_workgroup_id_z 0
		.amdhsa_system_sgpr_workgroup_info 0
		.amdhsa_system_vgpr_workitem_id 2
		.amdhsa_next_free_vgpr 254
		.amdhsa_next_free_sgpr 100
		.amdhsa_accum_offset 256
		.amdhsa_reserve_vcc 1
		.amdhsa_float_round_mode_32 0
		.amdhsa_float_round_mode_16_64 0
		.amdhsa_float_denorm_mode_32 3
		.amdhsa_float_denorm_mode_16_64 3
		.amdhsa_dx10_clamp 1
		.amdhsa_ieee_mode 1
		.amdhsa_fp16_overflow 0
		.amdhsa_tg_split 0
		.amdhsa_exception_fp_ieee_invalid_op 0
		.amdhsa_exception_fp_denorm_src 0
		.amdhsa_exception_fp_ieee_div_zero 0
		.amdhsa_exception_fp_ieee_overflow 0
		.amdhsa_exception_fp_ieee_underflow 0
		.amdhsa_exception_fp_ieee_inexact 0
		.amdhsa_exception_int_div_zero 0
	.end_amdhsa_kernel

amdhsa.kernels:
  - .agpr_count:     0
    .args:
      - .offset:         0
        .size:           1984
        .value_kind:     by_value
      - .offset:         1984
        .size:           4
        .value_kind:     hidden_block_count_x
      - .offset:         1988
        .size:           4
        .value_kind:     hidden_block_count_y
      - .offset:         1992
        .size:           4
        .value_kind:     hidden_block_count_z
      - .offset:         1996
        .size:           2
        .value_kind:     hidden_group_size_x
      - .offset:         1998
        .size:           2
        .value_kind:     hidden_group_size_y
      - .offset:         2000
        .size:           2
        .value_kind:     hidden_group_size_z
      - .offset:         2002
        .size:           2
        .value_kind:     hidden_remainder_x
      - .offset:         2004
        .size:           2
        .value_kind:     hidden_remainder_y
      - .offset:         2006
        .size:           2
        .value_kind:     hidden_remainder_z
      - .offset:         2024
        .size:           8
        .value_kind:     hidden_global_offset_x
      - .offset:         2032
        .size:           8
        .value_kind:     hidden_global_offset_y
      - .offset:         2040
        .size:           8
        .value_kind:     hidden_global_offset_z
      - .offset:         2048
        .size:           2
        .value_kind:     hidden_grid_dims
      - .offset:         2072
        .size:           8
        .value_kind:     hidden_multigrid_sync_arg
      - .offset:         2104
        .size:           4
        .value_kind:     hidden_dynamic_lds_size
    .group_segment_fixed_size: 0
    .kernarg_segment_align: 8
    .kernarg_segment_size: 2240
    .language:       OpenCL C
    .language_version:
      - 2
      - 0
    .max_flat_workgroup_size: 512
    .name:           _Z8yoco_fwd4Args
    .private_segment_fixed_size: 0
    .sgpr_count:     106
    .sgpr_spill_count: 0
    .symbol:         _Z8yoco_fwd4Args.kd
    .uniform_work_group_size: 1
    .uses_dynamic_stack: false
    .vgpr_count:     254
    .vgpr_spill_count: 0
    .wavefront_size: 64
